# norm<1>: hand-written pass 2/3 keeping x in spare VGPRs (no recompute), on top of K-loop barrier/priority edit
# speedup vs baseline: 1.0080x; 1.0080x over previous
; #define LAS __attribute__((address_space(3)))
; template <int MODE> ...
;     if (!xn_out) { xn_out = xn; rs_out = rs; }
;     LAS float* GP = (LAS float*)lds; LAS float* GN = (LAS float*)(lds + 16384); LAS float* GI = (LAS float*)(lds + 32768);
;     __syncthreads();
; #pragma unroll
;     for (int i = 0; i < 2; ++i) { const int o = 4 * (tid + NTHREADS * i);
;         if (MODE != 0) { *(LAS f32x4*)(GP + o) = *(const f32x4*)(gpost + o); const f32x4 g = *(const f32x4*)(gprev + o); *(LAS f32x4*)(GI + o) = (f32x4){1.f / g.x, 1.f / g.y, 1.f / g.z, 1.f / g.w}; }
;         if (MODE != 2) *(LAS f32x4*)(GN + o) = *(const f32x4*)(gpre + o); }
;     __syncthreads();
;     const int lo4 = 4 * lane;
; #pragma unroll 1
;     for (int row = gw; row < SEQ; row += NGW) {
.LBB0_772:
	s_cmp_gt_i32 s36, 6
	s_cselect_b64 s[6:7], -1, 0
	s_xor_b64 s[4:5], s[4:5], -1
	s_or_b64 s[4:5], s[6:7], s[4:5]
	s_and_b64 vcc, exec, s[4:5]
	s_cbranch_vccnz .LBB0_778
	s_mov_b64 s[12:13], 0
	v_mbcnt_lo_u32_b32 v2, -1, 0
	v_mbcnt_hi_u32_b32 v2, -1, v2
	s_load_dwordx4 s[4:7], s[0:1], 0x10
	s_load_dwordx2 s[8:9], s[0:1], 0x70
	v_lshlrev_b32_e32 v0, 2, v2
	v_lshl_add_u32 v24, s89, 8, v0
	v_ashrrev_i32_e32 v25, 31, v24
	v_lshlrev_b64 v[12:13], 2, v[24:25]
	v_add_u32_e32 v16, 0x800, v24
	s_waitcnt lgkmcnt(0)
	v_lshl_add_u64 v[8:9], s[4:5], 0, v[12:13]
	v_ashrrev_i32_e32 v17, 31, v16
	s_waitcnt vmcnt(0)
	s_barrier
	v_lshl_add_u64 v[4:5], s[6:7], 0, v[12:13]
	global_load_dwordx4 v[8:11], v[8:9], off
	v_lshl_add_u64 v[12:13], s[8:9], 0, v[12:13]
	v_lshlrev_b64 v[26:27], 2, v[16:17]
	global_load_dwordx4 v[4:7], v[4:5], off
	v_lshl_add_u64 v[16:17], s[6:7], 0, v[26:27]
	global_load_dwordx4 v[12:15], v[12:13], off
	v_lshl_add_u64 v[20:21], s[4:5], 0, v[26:27]
	global_load_dwordx4 v[16:19], v[16:17], off
	v_lshl_add_u32 v1, v24, 2, 0
	global_load_dwordx4 v[20:23], v[20:21], off
	v_lshl_add_u64 v[24:25], s[8:9], 0, v[26:27]
	global_load_dwordx4 v[24:27], v[24:25], off
	s_cmpk_gt_i32 s40, 0x1fff
	s_waitcnt vmcnt(5)
	v_div_scale_f32 v3, s[4:5], v8, v8, 1.0
	v_div_scale_f32 v29, s[8:9], v11, v11, 1.0
	s_waitcnt vmcnt(4)
	ds_write_b128 v1, v[4:7]
	v_div_scale_f32 v5, s[4:5], v9, v9, 1.0
	s_waitcnt vmcnt(3)
	ds_write_b128 v1, v[12:15] offset:16384
	v_rcp_f32_e32 v12, v3
	v_div_scale_f32 v7, s[6:7], v10, v10, 1.0
	v_rcp_f32_e32 v13, v5
	s_waitcnt vmcnt(2)
	ds_write_b128 v1, v[16:19] offset:8192
	s_waitcnt vmcnt(1)
	v_div_scale_f32 v16, s[10:11], v20, v20, 1.0
	v_rcp_f32_e32 v14, v7
	v_rcp_f32_e32 v19, v16
	v_rcp_f32_e32 v15, v29
	v_fma_f32 v32, -v3, v12, 1.0
	v_div_scale_f32 v4, vcc, 1.0, v8, 1.0
	v_fma_f32 v33, -v5, v13, 1.0
	v_fmac_f32_e32 v12, v32, v12
	v_div_scale_f32 v6, s[4:5], 1.0, v9, 1.0
	v_fma_f32 v34, -v7, v14, 1.0
	v_fmac_f32_e32 v13, v33, v13
	v_fma_f32 v32, -v16, v19, 1.0
	v_mul_f32_e32 v33, v4, v12
	v_div_scale_f32 v28, s[6:7], 1.0, v10, 1.0
	v_fma_f32 v35, -v29, v15, 1.0
	v_fmac_f32_e32 v14, v34, v14
	v_mul_f32_e32 v34, v6, v13
	v_fmac_f32_e32 v19, v32, v19
	v_fma_f32 v32, -v3, v33, v4
	v_div_scale_f32 v30, s[8:9], 1.0, v11, 1.0
	v_fmac_f32_e32 v15, v35, v15
	v_mul_f32_e32 v35, v28, v14
	v_fma_f32 v37, -v5, v34, v6
	v_fmac_f32_e32 v33, v32, v12
	v_div_scale_f32 v17, s[10:11], 1.0, v20, 1.0
	v_mul_f32_e32 v36, v30, v15
	v_fma_f32 v38, -v7, v35, v28
	v_fmac_f32_e32 v34, v37, v13
	v_fma_f32 v3, -v3, v33, v4
	v_div_scale_f32 v18, s[14:15], v21, v21, 1.0
	v_fma_f32 v39, -v29, v36, v30
	v_mul_f32_e32 v40, v17, v19
	v_fmac_f32_e32 v35, v38, v14
	v_fma_f32 v5, -v5, v34, v6
	v_div_fmas_f32 v3, v3, v12, v33
	s_mov_b64 vcc, s[4:5]
	v_rcp_f32_e32 v31, v18
	v_fmac_f32_e32 v36, v39, v15
	v_fma_f32 v32, -v16, v40, v17
	v_fma_f32 v6, -v7, v35, v28
	v_div_fixup_f32 v4, v3, v8, 1.0
	v_div_fmas_f32 v3, v5, v13, v34
	s_mov_b64 vcc, s[6:7]
	v_fma_f32 v7, -v29, v36, v30
	v_fmac_f32_e32 v40, v32, v19
	v_div_fixup_f32 v5, v3, v9, 1.0
	v_div_fmas_f32 v3, v6, v14, v35
	s_mov_b64 vcc, s[8:9]
	v_fma_f32 v12, -v16, v40, v17
	v_div_fixup_f32 v6, v3, v10, 1.0
	v_div_fmas_f32 v3, v7, v15, v36
	s_mov_b64 vcc, s[10:11]
	v_div_fixup_f32 v7, v3, v11, 1.0
	v_div_fmas_f32 v3, v12, v19, v40
	ds_write_b128 v1, v[4:7] offset:32768
	v_div_fixup_f32 v4, v3, v20, 1.0
	v_fma_f32 v3, -v18, v31, 1.0
	v_fmac_f32_e32 v31, v3, v31
	v_div_scale_f32 v3, vcc, 1.0, v21, 1.0
	v_mul_f32_e32 v5, v3, v31
	v_fma_f32 v6, -v18, v5, v3
	v_fmac_f32_e32 v5, v6, v31
	v_div_scale_f32 v6, s[4:5], v22, v22, 1.0
	v_rcp_f32_e32 v7, v6
	v_fma_f32 v3, -v18, v5, v3
	v_div_fmas_f32 v3, v3, v31, v5
	v_div_fixup_f32 v5, v3, v21, 1.0
	v_fma_f32 v3, -v6, v7, 1.0
	v_fmac_f32_e32 v7, v3, v7
	v_div_scale_f32 v3, vcc, 1.0, v22, 1.0
	v_mul_f32_e32 v8, v3, v7
	v_fma_f32 v9, -v6, v8, v3
	v_fmac_f32_e32 v8, v9, v7
	v_div_scale_f32 v9, s[4:5], v23, v23, 1.0
	v_rcp_f32_e32 v10, v9
	v_fma_f32 v3, -v6, v8, v3
	v_div_fmas_f32 v3, v3, v7, v8
	v_div_fixup_f32 v6, v3, v22, 1.0
	v_fma_f32 v3, -v9, v10, 1.0
	v_fmac_f32_e32 v10, v3, v10
	v_div_scale_f32 v3, vcc, 1.0, v23, 1.0
	v_mul_f32_e32 v7, v3, v10
	v_fma_f32 v8, -v9, v7, v3
	v_fmac_f32_e32 v7, v8, v10
	v_fma_f32 v3, -v9, v7, v3
	v_div_fmas_f32 v3, v3, v10, v7
	v_div_fixup_f32 v7, v3, v23, 1.0
	ds_write_b128 v1, v[4:7] offset:40960
	s_waitcnt vmcnt(0)
	ds_write_b128 v1, v[24:27] offset:24576
	s_waitcnt lgkmcnt(0)
	s_barrier
	s_cbranch_scc1 .LBB0_778
	s_load_dwordx2 s[6:7], s[0:1], 0xe8
	s_ashr_i32 s41, s40, 31
	s_lshl_b64 s[8:9], s[40:41], 2
	v_ashrrev_i32_e32 v1, 31, v0
	v_cmp_eq_u32_e64 s[4:5], 0, v2
	s_waitcnt lgkmcnt(0)
	s_add_u32 s8, s6, s8
	s_addc_u32 s9, s7, s9
	s_add_u32 s64, s8, 0x2c0000
	s_addc_u32 s65, s9, 0
	s_ashr_i32 s39, s38, 31
	s_lshl_b64 s[8:9], s[38:39], 2
	s_lshl_b64 s[10:11], s[40:41], 13
	s_add_u32 s6, s6, s10
	s_addc_u32 s7, s7, s11
	v_mbcnt_lo_u32_b32 v2, -1, 0
	v_lshl_add_u32 v71, v0, 2, 0
	v_lshl_add_u64 v[0:1], v[0:1], 1, s[6:7]
	s_lshl_b64 s[10:11], s[38:39], 13
	s_mov_b64 s[14:15], 0x3000000
	s_mov_b64 s[18:19], 0x3000200
	s_mov_b64 s[20:21], 0x3000400
	s_mov_b64 s[22:23], 0x3000600
	s_mov_b64 s[24:25], 0x3000800
	s_mov_b64 s[26:27], 0x3000a00
	s_mov_b64 s[42:43], 0x3000c00
	s_mov_b64 s[44:45], 0x3000e00
	s_mov_b64 s[46:47], 0x3001000
	s_mov_b32 s39, 0x3001000
	s_mov_b32 s41, 0x7001000
	s_mov_b64 s[48:49], 0x3001200
	s_mov_b64 s[50:51], 0x3001400
	s_mov_b64 s[52:53], 0x3001600
	s_mov_b64 s[54:55], 0x3001800
	s_mov_b64 s[56:57], 0x3001a00
	s_mov_b64 s[58:59], 0x3001c00
	s_mov_b64 s[60:61], 0x3001e00
	v_mov_b32_e32 v98, 0
	v_mov_b32_e32 v99, 0x358637bd
	s_mov_b32 s66, 0x800000
	v_mbcnt_hi_u32_b32 v100, -1, v2
	s_mov_b32 s67, s40
	s_mov_b32 s96, 0x3000000
	s_mov_b32 s97, 0x3001000
	s_branch .LBB0_776
; #define LAS __attribute__((address_space(3)))
; __device__ __forceinline__ unsigned pk2(float lo, float hi) { const f32x2c v = {lo, hi}; return __builtin_bit_cast(unsigned, __builtin_convertvector(v, bf16x2c)); }
; __device__ __forceinline__ float bflo(unsigned w) { return __uint_as_float(w << 16); }
; __device__ __forceinline__ float bfhi(unsigned w) { return __uint_as_float(w & 0xffff0000u); }
; #define LAUNDER_ROW(pw, hw) do { LAUNDER8(pw, 0); LAUNDER8(pw, 8); LAUNDER8(hw, 0); LAUNDER8(hw, 8); } while (0)
; template <int MODE> ...
;     ...
;                 LAUNDER_ROW(pw, hw);
;                 float ri2 = ri, rstdb = rstd; asm volatile("" : "+v"(ri2), "+v"(rstdb) :: "memory");
; #pragma unroll
;                 for (int j = 0; j < 16; ++j) { const f32x4 g = *(const LAS f32x4*)(GP + lo4 + 256 * j), gi = *(const LAS f32x4*)(GI + lo4 + 256 * j), gn = *(const LAS f32x4*)(GN + lo4 + 256 * j);
;                     f32x4 x;
;                     x.x = bflo(pw[j].x) * ri2 * gi.x + bflo(hw[j].x) * rstdb * g.x; x.y = bfhi(pw[j].x) * ri2 * gi.y + bfhi(hw[j].x) * rstdb * g.y;
;                     x.z = bflo(pw[j].y) * ri2 * gi.z + bflo(hw[j].y) * rstdb * g.z; x.w = bfhi(pw[j].y) * ri2 * gi.w + bfhi(hw[j].y) * rstdb * g.w;
;                     v2u w; w.x = pk2(x.x * rstd2 * gn.x, x.y * rstd2 * gn.y); w.y = pk2(x.z * rstd2 * gn.z, x.w * rstd2 * gn.w);
;                     *(v2u*)(pw_out + lo4 + 256 * j) = w;
;                     if (j & 1) __builtin_amdgcn_sched_barrier(0); }
.LBB0_775:
	s_or_b64 exec, exec, s[6:7]
	v_add_co_u32_e32 v224, vcc, s96, v66
	s_nop 1
	v_addc_co_u32_e32 v225, vcc, 0, v67, vcc
	v_add_co_u32_e32 v226, vcc, s97, v66
	s_nop 1
	v_addc_co_u32_e32 v227, vcc, 0, v67, vcc
	ds_read_b128 v[196:199], v71 offset:16384
	ds_read_b128 v[204:207], v71 offset:17408
	v_mul_f32_e32 v212, v70, v132
	v_mul_f32_e32 v213, v70, v133
	v_mul_f32_e32 v214, v70, v134
	v_mul_f32_e32 v215, v70, v135
	s_waitcnt lgkmcnt(1)
	v_mul_f32_e32 v212, v196, v212
	v_mul_f32_e32 v213, v197, v213
	v_mul_f32_e32 v214, v198, v214
	v_mul_f32_e32 v215, v199, v215
	v_cvt_pk_bf16_f32 v216, v212, v213
	v_cvt_pk_bf16_f32 v217, v214, v215
	global_store_dwordx2 v[224:225], v[216:217], off
	ds_read_b128 v[196:199], v71 offset:18432
	v_mul_f32_e32 v212, v70, v136
	v_mul_f32_e32 v213, v70, v137
	v_mul_f32_e32 v214, v70, v138
	v_mul_f32_e32 v215, v70, v139
	s_waitcnt lgkmcnt(1)
	v_mul_f32_e32 v212, v204, v212
	v_mul_f32_e32 v213, v205, v213
	v_mul_f32_e32 v214, v206, v214
	v_mul_f32_e32 v215, v207, v215
	v_cvt_pk_bf16_f32 v218, v212, v213
	v_cvt_pk_bf16_f32 v219, v214, v215
	global_store_dwordx2 v[224:225], v[218:219], off offset:512
	ds_read_b128 v[204:207], v71 offset:19456
	v_mul_f32_e32 v212, v70, v140
	v_mul_f32_e32 v213, v70, v141
	v_mul_f32_e32 v214, v70, v142
	v_mul_f32_e32 v215, v70, v143
	s_waitcnt lgkmcnt(1)
	v_mul_f32_e32 v212, v196, v212
	v_mul_f32_e32 v213, v197, v213
	v_mul_f32_e32 v214, v198, v214
	v_mul_f32_e32 v215, v199, v215
	v_cvt_pk_bf16_f32 v220, v212, v213
	v_cvt_pk_bf16_f32 v221, v214, v215
	global_store_dwordx2 v[224:225], v[220:221], off offset:1024
	ds_read_b128 v[196:199], v71 offset:20480
	v_mul_f32_e32 v212, v70, v144
	v_mul_f32_e32 v213, v70, v145
	v_mul_f32_e32 v214, v70, v146
	v_mul_f32_e32 v215, v70, v147
	s_waitcnt lgkmcnt(1)
	v_mul_f32_e32 v212, v204, v212
	v_mul_f32_e32 v213, v205, v213
	v_mul_f32_e32 v214, v206, v214
	v_mul_f32_e32 v215, v207, v215
	v_cvt_pk_bf16_f32 v222, v212, v213
	v_cvt_pk_bf16_f32 v223, v214, v215
	global_store_dwordx2 v[224:225], v[222:223], off offset:1536
	ds_read_b128 v[204:207], v71 offset:21504
	v_mul_f32_e32 v212, v70, v148
	v_mul_f32_e32 v213, v70, v149
	v_mul_f32_e32 v214, v70, v150
	v_mul_f32_e32 v215, v70, v151
	s_waitcnt lgkmcnt(1)
	v_mul_f32_e32 v212, v196, v212
	v_mul_f32_e32 v213, v197, v213
	v_mul_f32_e32 v214, v198, v214
	v_mul_f32_e32 v215, v199, v215
	v_cvt_pk_bf16_f32 v216, v212, v213
	v_cvt_pk_bf16_f32 v217, v214, v215
	global_store_dwordx2 v[224:225], v[216:217], off offset:2048
	ds_read_b128 v[196:199], v71 offset:22528
	v_mul_f32_e32 v212, v70, v152
	v_mul_f32_e32 v213, v70, v153
	v_mul_f32_e32 v214, v70, v154
	v_mul_f32_e32 v215, v70, v155
	s_waitcnt lgkmcnt(1)
	v_mul_f32_e32 v212, v204, v212
	v_mul_f32_e32 v213, v205, v213
	v_mul_f32_e32 v214, v206, v214
	v_mul_f32_e32 v215, v207, v215
	v_cvt_pk_bf16_f32 v218, v212, v213
	v_cvt_pk_bf16_f32 v219, v214, v215
	global_store_dwordx2 v[224:225], v[218:219], off offset:2560
	ds_read_b128 v[204:207], v71 offset:23552
	v_mul_f32_e32 v212, v70, v156
	v_mul_f32_e32 v213, v70, v157
	v_mul_f32_e32 v214, v70, v158
	v_mul_f32_e32 v215, v70, v159
	s_waitcnt lgkmcnt(1)
	v_mul_f32_e32 v212, v196, v212
	v_mul_f32_e32 v213, v197, v213
	v_mul_f32_e32 v214, v198, v214
	v_mul_f32_e32 v215, v199, v215
	v_cvt_pk_bf16_f32 v220, v212, v213
	v_cvt_pk_bf16_f32 v221, v214, v215
	global_store_dwordx2 v[224:225], v[220:221], off offset:3072
	ds_read_b128 v[196:199], v71 offset:24576
	v_mul_f32_e32 v212, v70, v160
	v_mul_f32_e32 v213, v70, v161
	v_mul_f32_e32 v214, v70, v162
	v_mul_f32_e32 v215, v70, v163
	s_waitcnt lgkmcnt(1)
	v_mul_f32_e32 v212, v204, v212
	v_mul_f32_e32 v213, v205, v213
	v_mul_f32_e32 v214, v206, v214
	v_mul_f32_e32 v215, v207, v215
	v_cvt_pk_bf16_f32 v222, v212, v213
	v_cvt_pk_bf16_f32 v223, v214, v215
	global_store_dwordx2 v[224:225], v[222:223], off offset:3584
	ds_read_b128 v[204:207], v71 offset:25600
	v_mul_f32_e32 v212, v70, v164
	v_mul_f32_e32 v213, v70, v165
	v_mul_f32_e32 v214, v70, v166
	v_mul_f32_e32 v215, v70, v167
	s_waitcnt lgkmcnt(1)
	v_mul_f32_e32 v212, v196, v212
	v_mul_f32_e32 v213, v197, v213
	v_mul_f32_e32 v214, v198, v214
	v_mul_f32_e32 v215, v199, v215
	v_cvt_pk_bf16_f32 v216, v212, v213
	v_cvt_pk_bf16_f32 v217, v214, v215
	global_store_dwordx2 v[226:227], v[216:217], off
	ds_read_b128 v[196:199], v71 offset:26624
	v_mul_f32_e32 v212, v70, v168
	v_mul_f32_e32 v213, v70, v169
	v_mul_f32_e32 v214, v70, v170
	v_mul_f32_e32 v215, v70, v171
	s_waitcnt lgkmcnt(1)
	v_mul_f32_e32 v212, v204, v212
	v_mul_f32_e32 v213, v205, v213
	v_mul_f32_e32 v214, v206, v214
	v_mul_f32_e32 v215, v207, v215
	v_cvt_pk_bf16_f32 v218, v212, v213
	v_cvt_pk_bf16_f32 v219, v214, v215
	global_store_dwordx2 v[226:227], v[218:219], off offset:512
	ds_read_b128 v[204:207], v71 offset:27648
	v_mul_f32_e32 v212, v70, v172
	v_mul_f32_e32 v213, v70, v173
	v_mul_f32_e32 v214, v70, v174
	v_mul_f32_e32 v215, v70, v175
	s_waitcnt lgkmcnt(1)
	v_mul_f32_e32 v212, v196, v212
	v_mul_f32_e32 v213, v197, v213
	v_mul_f32_e32 v214, v198, v214
	v_mul_f32_e32 v215, v199, v215
	v_cvt_pk_bf16_f32 v220, v212, v213
	v_cvt_pk_bf16_f32 v221, v214, v215
	global_store_dwordx2 v[226:227], v[220:221], off offset:1024
	ds_read_b128 v[196:199], v71 offset:28672
	v_mul_f32_e32 v212, v70, v176
	v_mul_f32_e32 v213, v70, v177
	v_mul_f32_e32 v214, v70, v178
	v_mul_f32_e32 v215, v70, v179
	s_waitcnt lgkmcnt(1)
	v_mul_f32_e32 v212, v204, v212
	v_mul_f32_e32 v213, v205, v213
	v_mul_f32_e32 v214, v206, v214
	v_mul_f32_e32 v215, v207, v215
	v_cvt_pk_bf16_f32 v222, v212, v213
	v_cvt_pk_bf16_f32 v223, v214, v215
	global_store_dwordx2 v[226:227], v[222:223], off offset:1536
	ds_read_b128 v[204:207], v71 offset:29696
	v_mul_f32_e32 v212, v70, v180
	v_mul_f32_e32 v213, v70, v181
	v_mul_f32_e32 v214, v70, v182
	v_mul_f32_e32 v215, v70, v183
	s_waitcnt lgkmcnt(1)
; #define LAS __attribute__((address_space(3)))
; __device__ __forceinline__ unsigned pk2(float lo, float hi) { const f32x2c v = {lo, hi}; return __builtin_bit_cast(unsigned, __builtin_convertvector(v, bf16x2c)); }
; __device__ __forceinline__ float bflo(unsigned w) { return __uint_as_float(w << 16); }
; __device__ __forceinline__ float bfhi(unsigned w) { return __uint_as_float(w & 0xffff0000u); }
; #define LAUNDER_ROW(pw, hw) do { LAUNDER8(pw, 0); LAUNDER8(pw, 8); LAUNDER8(hw, 0); LAUNDER8(hw, 8); } while (0)
; template <int MODE> ...
;     ...
;             const bf16* pr = xn + (size_t)row * DM; bf16* pw_out = xn_out + (size_t)row * DM; const bf16* hr = hb + (size_t)row * DM;
;             v2u pw[16], hw[16]; float ss = 0.f;
; #pragma unroll
;             for (int j = 0; j < 16; ++j) { pw[j] = *(const v2u*)(pr + lo4 + 256 * j); hw[j] = *(const v2u*)(hr + lo4 + 256 * j); }
;             const float ri = 1.f / rs[row];
; #pragma unroll
;             for (int j = 0; j < 16; ++j) { const float a = bflo(hw[j].x), b = bfhi(hw[j].x), c = bflo(hw[j].y), d = bfhi(hw[j].y); ss += a * a + b * b + c * c + d * d; }
;     ...
;                 LAUNDER_ROW(pw, hw);
;                 float ri2 = ri, rstdb = rstd; asm volatile("" : "+v"(ri2), "+v"(rstdb) :: "memory");
; #pragma unroll
;                 for (int j = 0; j < 16; ++j) { const f32x4 g = *(const LAS f32x4*)(GP + lo4 + 256 * j), gi = *(const LAS f32x4*)(GI + lo4 + 256 * j), gn = *(const LAS f32x4*)(GN + lo4 + 256 * j);
;                     f32x4 x;
;                     x.x = bflo(pw[j].x) * ri2 * gi.x + bflo(hw[j].x) * rstdb * g.x; x.y = bfhi(pw[j].x) * ri2 * gi.y + bfhi(hw[j].x) * rstdb * g.y;
;                     x.z = bflo(pw[j].y) * ri2 * gi.z + bflo(hw[j].y) * rstdb * g.z; x.w = bfhi(pw[j].y) * ri2 * gi.w + bfhi(hw[j].y) * rstdb * g.w;
;                     v2u w; w.x = pk2(x.x * rstd2 * gn.x, x.y * rstd2 * gn.y); w.y = pk2(x.z * rstd2 * gn.z, x.w * rstd2 * gn.w);
;                     *(v2u*)(pw_out + lo4 + 256 * j) = w;
;                     if (j & 1) __builtin_amdgcn_sched_barrier(0); }
	v_mul_f32_e32 v212, v196, v212
	v_mul_f32_e32 v213, v197, v213
	v_mul_f32_e32 v214, v198, v214
	v_mul_f32_e32 v215, v199, v215
	v_cvt_pk_bf16_f32 v216, v212, v213
	v_cvt_pk_bf16_f32 v217, v214, v215
	global_store_dwordx2 v[226:227], v[216:217], off offset:2048
	ds_read_b128 v[196:199], v71 offset:30720
	v_mul_f32_e32 v212, v70, v184
	v_mul_f32_e32 v213, v70, v185
	v_mul_f32_e32 v214, v70, v186
	v_mul_f32_e32 v215, v70, v187
	s_waitcnt lgkmcnt(1)
	v_mul_f32_e32 v212, v204, v212
	v_mul_f32_e32 v213, v205, v213
	v_mul_f32_e32 v214, v206, v214
	v_mul_f32_e32 v215, v207, v215
	v_cvt_pk_bf16_f32 v218, v212, v213
	v_cvt_pk_bf16_f32 v219, v214, v215
	global_store_dwordx2 v[226:227], v[218:219], off offset:2560
	ds_read_b128 v[204:207], v71 offset:31744
	v_mul_f32_e32 v212, v70, v188
	v_mul_f32_e32 v213, v70, v189
	v_mul_f32_e32 v214, v70, v190
	v_mul_f32_e32 v215, v70, v191
	s_waitcnt lgkmcnt(1)
	v_mul_f32_e32 v212, v196, v212
	v_mul_f32_e32 v213, v197, v213
	v_mul_f32_e32 v214, v198, v214
	v_mul_f32_e32 v215, v199, v215
	v_cvt_pk_bf16_f32 v220, v212, v213
	v_cvt_pk_bf16_f32 v221, v214, v215
	global_store_dwordx2 v[226:227], v[220:221], off offset:3072
	v_mul_f32_e32 v212, v70, v192
	v_mul_f32_e32 v213, v70, v193
	v_mul_f32_e32 v214, v70, v194
	v_mul_f32_e32 v215, v70, v195
	s_waitcnt lgkmcnt(0)
	v_mul_f32_e32 v212, v204, v212
	v_mul_f32_e32 v213, v205, v213
	v_mul_f32_e32 v214, v206, v214
	v_mul_f32_e32 v215, v207, v215
	v_cvt_pk_bf16_f32 v222, v212, v213
	v_cvt_pk_bf16_f32 v223, v214, v215
	global_store_dwordx2 v[226:227], v[222:223], off offset:3584
	s_add_i32 s67, s67, s38
	s_add_u32 s64, s64, s8
	s_addc_u32 s65, s65, s9
	s_cmpk_lt_i32 s67, 0x2000
	v_lshl_add_u64 v[0:1], v[0:1], 0, s[10:11]
	s_cbranch_scc0 .LBB0_778
.LBB0_776:
	v_lshl_add_u64 v[66:67], v[0:1], 0, s[12:13]
	v_add_co_u32_e32 v36, vcc, 0x3000000, v66
	s_mov_b64 s[6:7], vcc
	v_add_co_u32_e32 v2, vcc, 0x7000000, v66
	s_add_u32 s62, s64, s12
	s_nop 0
	v_addc_co_u32_e32 v3, vcc, 0, v67, vcc
	global_load_dwordx2 v[60:61], v[2:3], off
	global_load_dwordx2 v[54:55], v[2:3], off offset:512
	global_load_dwordx2 v[52:53], v[2:3], off offset:1024
	global_load_dwordx2 v[48:49], v[2:3], off offset:1536
	global_load_dwordx2 v[44:45], v[2:3], off offset:2048
	global_load_dwordx2 v[42:43], v[2:3], off offset:2560
	v_add_co_u32_e32 v4, vcc, s39, v66
	s_addc_u32 s63, s65, s13
	s_nop 0
	v_addc_co_u32_e32 v5, vcc, 0, v67, vcc
	v_add_co_u32_e32 v40, vcc, s41, v66
	s_waitcnt vmcnt(5)
	v_and_b32_e32 v69, 0xffff0000, v60
	v_addc_co_u32_e32 v41, vcc, 0, v67, vcc
	v_addc_co_u32_e64 v37, vcc, 0, v67, s[6:7]
	global_load_dwordx2 v[38:39], v[2:3], off offset:3072
	global_load_dwordx2 v[30:31], v[4:5], off
	global_load_dwordx2 v[26:27], v[4:5], off offset:512
	global_load_dwordx2 v[22:23], v[4:5], off offset:1024
	global_load_dwordx2 v[18:19], v[4:5], off offset:1536
	global_load_dwordx2 v[32:33], v[40:41], off
	global_load_dwordx2 v[28:29], v[40:41], off offset:512
	global_load_dwordx2 v[24:25], v[40:41], off offset:1024
	global_load_dwordx2 v[20:21], v[40:41], off offset:1536
	global_load_dwordx2 v[34:35], v[2:3], off offset:3584
	global_load_dwordx2 v[14:15], v[4:5], off offset:2048
	global_load_dwordx2 v[10:11], v[4:5], off offset:2560
	global_load_dwordx2 v[6:7], v[4:5], off offset:3072
	s_nop 0
	global_load_dwordx2 v[2:3], v[4:5], off offset:3584
	global_load_dwordx2 v[16:17], v[40:41], off offset:2048
	global_load_dwordx2 v[12:13], v[40:41], off offset:2560
	global_load_dwordx2 v[8:9], v[40:41], off offset:3072
	s_nop 0
	global_load_dwordx2 v[4:5], v[40:41], off offset:3584
	global_load_dword v78, v98, s[62:63]
	global_load_dwordx2 v[64:65], v[36:37], off
	global_load_dwordx2 v[62:63], v[36:37], off offset:512
	global_load_dwordx2 v[58:59], v[36:37], off offset:1024
	global_load_dwordx2 v[56:57], v[36:37], off offset:1536
	global_load_dwordx2 v[50:51], v[36:37], off offset:2048
	global_load_dwordx2 v[46:47], v[36:37], off offset:2560
	global_load_dwordx2 v[40:41], v[36:37], off offset:3072
	s_nop 0
	global_load_dwordx2 v[36:37], v[36:37], off offset:3584
	s_waitcnt vmcnt(31)
	v_and_b32_e32 v74, 0xffff0000, v54
	v_lshlrev_b32_e32 v68, 16, v60
	v_lshlrev_b32_e32 v73, 16, v54
	v_mul_f32_e32 v69, v69, v69
	v_mul_f32_e32 v74, v74, v74
	v_lshlrev_b32_e32 v70, 16, v61
	v_lshlrev_b32_e32 v75, 16, v55
	s_waitcnt vmcnt(30)
	v_and_b32_e32 v79, 0xffff0000, v52
	v_fmac_f32_e32 v69, v68, v68
	v_fmac_f32_e32 v74, v73, v73
	v_and_b32_e32 v72, 0xffff0000, v61
	v_and_b32_e32 v76, 0xffff0000, v55
	v_lshlrev_b32_e32 v77, 16, v52
	s_waitcnt vmcnt(29)
	v_and_b32_e32 v83, 0xffff0000, v48
	s_waitcnt vmcnt(28)
	v_and_b32_e32 v87, 0xffff0000, v44
	v_mul_f32_e32 v79, v79, v79
	v_fmac_f32_e32 v69, v70, v70
	v_fmac_f32_e32 v74, v75, v75
	v_lshlrev_b32_e32 v80, 16, v53
	v_lshlrev_b32_e32 v82, 16, v48
	v_lshlrev_b32_e32 v86, 16, v44
	v_mul_f32_e32 v83, v83, v83
	v_fmac_f32_e32 v79, v77, v77
	v_fmac_f32_e32 v69, v72, v72
	v_fmac_f32_e32 v74, v76, v76
	v_mul_f32_e32 v72, v87, v87
	v_and_b32_e32 v81, 0xffff0000, v53
	v_lshlrev_b32_e32 v84, 16, v49
	v_fmac_f32_e32 v83, v82, v82
	v_fmac_f32_e32 v79, v80, v80
	v_add_f32_e32 v68, v69, v74
	v_lshlrev_b32_e32 v69, 16, v45
	v_fmac_f32_e32 v72, v86, v86
	v_and_b32_e32 v85, 0xffff0000, v49
	v_fmac_f32_e32 v83, v84, v84
	v_fmac_f32_e32 v79, v81, v81
	v_and_b32_e32 v70, 0xffff0000, v45
	v_fmac_f32_e32 v72, v69, v69
	v_fmac_f32_e32 v83, v85, v85
	v_add_f32_e32 v68, v68, v79
	v_fmac_f32_e32 v72, v70, v70
	s_waitcnt vmcnt(27)
; #define LAS __attribute__((address_space(3)))
; __device__ __forceinline__ float bflo(unsigned w) { return __uint_as_float(w << 16); }
; __device__ __forceinline__ float bfhi(unsigned w) { return __uint_as_float(w & 0xffff0000u); }
; #define LAUNDER_ROW(pw, hw) do { LAUNDER8(pw, 0); LAUNDER8(pw, 8); LAUNDER8(hw, 0); LAUNDER8(hw, 8); } while (0)
; template <int MODE> ...
;     ...
;             const float ri = 1.f / rs[row];
; #pragma unroll
;             for (int j = 0; j < 16; ++j) { const float a = bflo(hw[j].x), b = bfhi(hw[j].x), c = bflo(hw[j].y), d = bfhi(hw[j].y); ss += a * a + b * b + c * c + d * d; }
;             const float rstd = rsqrtf(wave_sum(ss) * (1.f / DM) + EPS);
;             asm volatile("" ::: "memory");
;             LAUNDER_ROW(pw, hw);
;             float ss2 = 0.f;
; #pragma unroll
;             for (int j = 0; j < 16; ++j) { const f32x4 g = *(const LAS f32x4*)(GP + lo4 + 256 * j), gi = *(const LAS f32x4*)(GI + lo4 + 256 * j);
;                 f32x4 x;
;                 x.x = bflo(pw[j].x) * ri * gi.x + bflo(hw[j].x) * rstd * g.x; x.y = bfhi(pw[j].x) * ri * gi.y + bfhi(hw[j].x) * rstd * g.y;
;                 x.z = bflo(pw[j].y) * ri * gi.z + bflo(hw[j].y) * rstd * g.z; x.w = bfhi(pw[j].y) * ri * gi.w + bfhi(hw[j].y) * rstd * g.w;
	v_and_b32_e32 v70, 0xffff0000, v42
	v_add_f32_e32 v68, v68, v83
	v_lshlrev_b32_e32 v69, 16, v42
	v_mul_f32_e32 v70, v70, v70
	v_add_f32_e32 v68, v68, v72
	v_lshlrev_b32_e32 v72, 16, v43
	v_fmac_f32_e32 v70, v69, v69
	v_and_b32_e32 v73, 0xffff0000, v43
	v_fmac_f32_e32 v70, v72, v72
	v_fmac_f32_e32 v70, v73, v73
	v_add_f32_e32 v68, v68, v70
	s_waitcnt vmcnt(26)
	v_and_b32_e32 v70, 0xffff0000, v38
	v_lshlrev_b32_e32 v69, 16, v38
	v_mul_f32_e32 v70, v70, v70
	v_lshlrev_b32_e32 v72, 16, v39
	v_fmac_f32_e32 v70, v69, v69
	v_and_b32_e32 v73, 0xffff0000, v39
	v_fmac_f32_e32 v70, v72, v72
	v_fmac_f32_e32 v70, v73, v73
	v_add_f32_e32 v68, v68, v70
	s_waitcnt vmcnt(17)
	v_and_b32_e32 v70, 0xffff0000, v34
	v_lshlrev_b32_e32 v69, 16, v34
	v_mul_f32_e32 v70, v70, v70
	v_lshlrev_b32_e32 v72, 16, v35
	v_fmac_f32_e32 v70, v69, v69
	v_and_b32_e32 v73, 0xffff0000, v35
	v_fmac_f32_e32 v70, v72, v72
	v_fmac_f32_e32 v70, v73, v73
	v_add_f32_e32 v68, v68, v70
	v_and_b32_e32 v70, 0xffff0000, v32
	v_lshlrev_b32_e32 v69, 16, v32
	v_mul_f32_e32 v70, v70, v70
	v_lshlrev_b32_e32 v72, 16, v33
	v_fmac_f32_e32 v70, v69, v69
	v_and_b32_e32 v73, 0xffff0000, v33
	v_fmac_f32_e32 v70, v72, v72
	v_fmac_f32_e32 v70, v73, v73
	v_add_f32_e32 v68, v68, v70
	v_and_b32_e32 v70, 0xffff0000, v28
	v_lshlrev_b32_e32 v69, 16, v28
	v_mul_f32_e32 v70, v70, v70
	v_lshlrev_b32_e32 v72, 16, v29
	v_fmac_f32_e32 v70, v69, v69
	v_and_b32_e32 v73, 0xffff0000, v29
	v_fmac_f32_e32 v70, v72, v72
	v_fmac_f32_e32 v70, v73, v73
	v_add_f32_e32 v68, v68, v70
	v_and_b32_e32 v70, 0xffff0000, v24
	v_lshlrev_b32_e32 v69, 16, v24
	v_mul_f32_e32 v70, v70, v70
	v_lshlrev_b32_e32 v72, 16, v25
	v_fmac_f32_e32 v70, v69, v69
	v_and_b32_e32 v73, 0xffff0000, v25
	v_fmac_f32_e32 v70, v72, v72
	v_fmac_f32_e32 v70, v73, v73
	v_add_f32_e32 v68, v68, v70
	v_and_b32_e32 v70, 0xffff0000, v20
	v_lshlrev_b32_e32 v69, 16, v20
	v_mul_f32_e32 v70, v70, v70
	v_lshlrev_b32_e32 v72, 16, v21
	v_fmac_f32_e32 v70, v69, v69
	v_and_b32_e32 v73, 0xffff0000, v21
	v_fmac_f32_e32 v70, v72, v72
	v_fmac_f32_e32 v70, v73, v73
	s_waitcnt vmcnt(11)
	v_and_b32_e32 v73, 0xffff0000, v12
	v_and_b32_e32 v72, 0xffff0000, v16
	v_add_f32_e32 v70, v68, v70
	v_lshlrev_b32_e32 v69, 16, v12
	v_lshlrev_b32_e32 v68, 16, v16
	v_pk_mul_f32 v[72:73], v[72:73], v[72:73]
	v_lshlrev_b32_e32 v75, 16, v13
	v_lshlrev_b32_e32 v74, 16, v17
	v_pk_fma_f32 v[68:69], v[68:69], v[68:69], v[72:73]
	v_and_b32_e32 v77, 0xffff0000, v13
	v_and_b32_e32 v76, 0xffff0000, v17
	v_pk_fma_f32 v[68:69], v[74:75], v[74:75], v[68:69]
	s_waitcnt vmcnt(9)
	v_and_b32_e32 v73, 0xffff0000, v4
	v_pk_fma_f32 v[68:69], v[76:77], v[76:77], v[68:69]
	v_and_b32_e32 v72, 0xffff0000, v8
	v_add_f32_e32 v68, v70, v68
	v_add_f32_e32 v70, v68, v69
	v_lshlrev_b32_e32 v69, 16, v4
	v_lshlrev_b32_e32 v68, 16, v8
	v_pk_mul_f32 v[72:73], v[72:73], v[72:73]
	v_lshlrev_b32_e32 v75, 16, v5
	v_lshlrev_b32_e32 v74, 16, v9
	v_pk_fma_f32 v[68:69], v[68:69], v[68:69], v[72:73]
	v_and_b32_e32 v77, 0xffff0000, v5
	v_and_b32_e32 v76, 0xffff0000, v9
	v_pk_fma_f32 v[68:69], v[74:75], v[74:75], v[68:69]
	s_waitcnt vmcnt(0)
	v_pk_fma_f32 v[68:69], v[76:77], v[76:77], v[68:69]
	v_div_scale_f32 v77, s[6:7], v78, v78, 1.0
	v_add_f32_e32 v68, v70, v68
	v_add_f32_e32 v68, v68, v69
	v_and_b32_e32 v69, 64, v100
	v_add_u32_e32 v69, 64, v69
	v_xor_b32_e32 v70, 1, v100
	v_cmp_lt_i32_e32 vcc, v70, v69
	v_rcp_f32_e32 v79, v77
	v_lshlrev_b32_e32 v86, 16, v60
	v_cndmask_b32_e32 v70, v100, v70, vcc
	v_lshlrev_b32_e32 v70, 2, v70
	ds_bpermute_b32 v72, v70, v68
	v_fma_f32 v80, -v77, v79, 1.0
	v_fmac_f32_e32 v79, v80, v79
	s_waitcnt lgkmcnt(0)
	v_add_f32_e32 v68, v68, v72
	v_xor_b32_e32 v72, 2, v100
	v_cmp_lt_i32_e32 vcc, v72, v69
	s_nop 1
	v_cndmask_b32_e32 v72, v100, v72, vcc
	v_lshlrev_b32_e32 v72, 2, v72
	ds_bpermute_b32 v73, v72, v68
	s_waitcnt lgkmcnt(0)
	v_add_f32_e32 v68, v68, v73
	v_xor_b32_e32 v73, 4, v100
	v_cmp_lt_i32_e32 vcc, v73, v69
	s_nop 1
	v_cndmask_b32_e32 v73, v100, v73, vcc
	v_lshlrev_b32_e32 v73, 2, v73
	ds_bpermute_b32 v74, v73, v68
	s_waitcnt lgkmcnt(0)
	v_add_f32_e32 v68, v68, v74
	v_xor_b32_e32 v74, 8, v100
	v_cmp_lt_i32_e32 vcc, v74, v69
	s_nop 1
	v_cndmask_b32_e32 v74, v100, v74, vcc
	v_lshlrev_b32_e32 v74, 2, v74
	ds_bpermute_b32 v75, v74, v68
	s_waitcnt lgkmcnt(0)
	v_add_f32_e32 v68, v68, v75
	v_xor_b32_e32 v75, 16, v100
	v_cmp_lt_i32_e32 vcc, v75, v69
	s_nop 1
	v_cndmask_b32_e32 v75, v100, v75, vcc
	v_lshlrev_b32_e32 v75, 2, v75
	ds_bpermute_b32 v76, v75, v68
	v_div_scale_f32 v80, vcc, 1.0, v78, 1.0
	v_mul_f32_e32 v81, v80, v79
	v_fma_f32 v82, -v77, v81, v80
	s_waitcnt lgkmcnt(0)
	v_add_f32_e32 v68, v68, v76
	v_xor_b32_e32 v76, 32, v100
	v_cmp_lt_i32_e64 s[6:7], v76, v69
	v_fmac_f32_e32 v81, v82, v79
	v_fma_f32 v77, -v77, v81, v80
	v_cndmask_b32_e64 v69, v100, v76, s[6:7]
	v_lshlrev_b32_e32 v76, 2, v69
	ds_bpermute_b32 v69, v76, v68
	s_waitcnt lgkmcnt(0)
	v_add_f32_e32 v68, v68, v69
	v_fmamk_f32 v68, v68, 0x39800000, v99
	v_mul_f32_e32 v69, 0x4b800000, v68
	v_cmp_gt_f32_e64 s[6:7], s66, v68
	s_nop 1
	v_cndmask_b32_e64 v68, v68, v69, s[6:7]
	v_rsq_f32_e32 v69, v68
	v_div_fmas_f32 v68, v77, v79, v81
	v_div_fixup_f32 v68, v68, v78, 1.0
	v_mul_f32_e32 v77, 0x45800000, v69
	v_cndmask_b32_e64 v69, v69, v77, s[6:7]
	ds_read_b128 v[196:199], v71
	ds_read_b128 v[200:203], v71 offset:32768
	ds_read_b128 v[204:207], v71 offset:1024
	ds_read_b128 v[208:211], v71 offset:33792
	v_lshlrev_b32_e32 v212, 16, v64
	v_and_b32_e32 v213, 0xffff0000, v64
	v_lshlrev_b32_e32 v214, 16, v65
	v_and_b32_e32 v215, 0xffff0000, v65
	v_lshlrev_b32_e32 v216, 16, v60
	v_and_b32_e32 v217, 0xffff0000, v60
	v_lshlrev_b32_e32 v218, 16, v61
	v_and_b32_e32 v219, 0xffff0000, v61
	v_mul_f32_e32 v212, v68, v212
	v_mul_f32_e32 v213, v68, v213
	v_mul_f32_e32 v214, v68, v214
	v_mul_f32_e32 v215, v68, v215
	v_mul_f32_e32 v216, v69, v216
	v_mul_f32_e32 v217, v69, v217
	v_mul_f32_e32 v218, v69, v218
	v_mul_f32_e32 v219, v69, v219
	s_waitcnt lgkmcnt(2)
; #define LAS __attribute__((address_space(3)))
; __device__ __forceinline__ float bflo(unsigned w) { return __uint_as_float(w << 16); }
; __device__ __forceinline__ float bfhi(unsigned w) { return __uint_as_float(w & 0xffff0000u); }
; template <int MODE> ...
;     ...
;             for (int j = 0; j < 16; ++j) { const f32x4 g = *(const LAS f32x4*)(GP + lo4 + 256 * j), gi = *(const LAS f32x4*)(GI + lo4 + 256 * j);
;                 f32x4 x;
;                 x.x = bflo(pw[j].x) * ri * gi.x + bflo(hw[j].x) * rstd * g.x; x.y = bfhi(pw[j].x) * ri * gi.y + bfhi(hw[j].x) * rstd * g.y;
;                 x.z = bflo(pw[j].y) * ri * gi.z + bflo(hw[j].y) * rstd * g.z; x.w = bfhi(pw[j].y) * ri * gi.w + bfhi(hw[j].y) * rstd * g.w;
;                 if (MODE == 2) *(f32x4*)(xout + (size_t)row * DM + lo4 + 256 * j) = x;
;                 else ss2 += x.x * x.x + x.y * x.y + x.z * x.z + x.w * x.w;
;                 if (j & 1) __builtin_amdgcn_sched_barrier(0); }
	v_mul_f32_e32 v132, v212, v200
	v_mul_f32_e32 v133, v213, v201
	v_mul_f32_e32 v134, v214, v202
	v_mul_f32_e32 v135, v215, v203
	v_fmac_f32_e32 v132, v196, v216
	v_fmac_f32_e32 v133, v197, v217
	v_fmac_f32_e32 v134, v198, v218
	v_fmac_f32_e32 v135, v199, v219
	v_mul_f32_e32 v77, v133, v133
	v_fmac_f32_e32 v77, v132, v132
	v_fmac_f32_e32 v77, v134, v134
	v_fmac_f32_e32 v77, v135, v135
	ds_read_b128 v[196:199], v71 offset:2048
	ds_read_b128 v[200:203], v71 offset:34816
	v_lshlrev_b32_e32 v212, 16, v62
	v_and_b32_e32 v213, 0xffff0000, v62
	v_lshlrev_b32_e32 v214, 16, v63
	v_and_b32_e32 v215, 0xffff0000, v63
	v_lshlrev_b32_e32 v216, 16, v54
	v_and_b32_e32 v217, 0xffff0000, v54
	v_lshlrev_b32_e32 v218, 16, v55
	v_and_b32_e32 v219, 0xffff0000, v55
	v_mul_f32_e32 v212, v68, v212
	v_mul_f32_e32 v213, v68, v213
	v_mul_f32_e32 v214, v68, v214
	v_mul_f32_e32 v215, v68, v215
	v_mul_f32_e32 v216, v69, v216
	v_mul_f32_e32 v217, v69, v217
	v_mul_f32_e32 v218, v69, v218
	v_mul_f32_e32 v219, v69, v219
	s_waitcnt lgkmcnt(2)
	v_mul_f32_e32 v136, v212, v208
	v_mul_f32_e32 v137, v213, v209
	v_mul_f32_e32 v138, v214, v210
	v_mul_f32_e32 v139, v215, v211
	v_fmac_f32_e32 v136, v204, v216
	v_fmac_f32_e32 v137, v205, v217
	v_fmac_f32_e32 v138, v206, v218
	v_fmac_f32_e32 v139, v207, v219
	v_mul_f32_e32 v212, v137, v137
	v_fmac_f32_e32 v212, v136, v136
	v_fmac_f32_e32 v212, v138, v138
	v_fmac_f32_e32 v212, v139, v139
	v_add_f32_e32 v77, v77, v212
	ds_read_b128 v[204:207], v71 offset:3072
	ds_read_b128 v[208:211], v71 offset:35840
	v_lshlrev_b32_e32 v212, 16, v58
	v_and_b32_e32 v213, 0xffff0000, v58
	v_lshlrev_b32_e32 v214, 16, v59
	v_and_b32_e32 v215, 0xffff0000, v59
	v_lshlrev_b32_e32 v216, 16, v52
	v_and_b32_e32 v217, 0xffff0000, v52
	v_lshlrev_b32_e32 v218, 16, v53
	v_and_b32_e32 v219, 0xffff0000, v53
	v_mul_f32_e32 v212, v68, v212
	v_mul_f32_e32 v213, v68, v213
	v_mul_f32_e32 v214, v68, v214
	v_mul_f32_e32 v215, v68, v215
	v_mul_f32_e32 v216, v69, v216
	v_mul_f32_e32 v217, v69, v217
	v_mul_f32_e32 v218, v69, v218
	v_mul_f32_e32 v219, v69, v219
	s_waitcnt lgkmcnt(2)
	v_mul_f32_e32 v140, v212, v200
	v_mul_f32_e32 v141, v213, v201
	v_mul_f32_e32 v142, v214, v202
	v_mul_f32_e32 v143, v215, v203
	v_fmac_f32_e32 v140, v196, v216
	v_fmac_f32_e32 v141, v197, v217
	v_fmac_f32_e32 v142, v198, v218
	v_fmac_f32_e32 v143, v199, v219
	v_mul_f32_e32 v212, v141, v141
	v_fmac_f32_e32 v212, v140, v140
	v_fmac_f32_e32 v212, v142, v142
	v_fmac_f32_e32 v212, v143, v143
	v_add_f32_e32 v77, v77, v212
	ds_read_b128 v[196:199], v71 offset:4096
	ds_read_b128 v[200:203], v71 offset:36864
	v_lshlrev_b32_e32 v212, 16, v56
	v_and_b32_e32 v213, 0xffff0000, v56
	v_lshlrev_b32_e32 v214, 16, v57
	v_and_b32_e32 v215, 0xffff0000, v57
	v_lshlrev_b32_e32 v216, 16, v48
	v_and_b32_e32 v217, 0xffff0000, v48
	v_lshlrev_b32_e32 v218, 16, v49
	v_and_b32_e32 v219, 0xffff0000, v49
	v_mul_f32_e32 v212, v68, v212
	v_mul_f32_e32 v213, v68, v213
	v_mul_f32_e32 v214, v68, v214
	v_mul_f32_e32 v215, v68, v215
	v_mul_f32_e32 v216, v69, v216
	v_mul_f32_e32 v217, v69, v217
	v_mul_f32_e32 v218, v69, v218
	v_mul_f32_e32 v219, v69, v219
	s_waitcnt lgkmcnt(2)
	v_mul_f32_e32 v144, v212, v208
	v_mul_f32_e32 v145, v213, v209
	v_mul_f32_e32 v146, v214, v210
	v_mul_f32_e32 v147, v215, v211
	v_fmac_f32_e32 v144, v204, v216
	v_fmac_f32_e32 v145, v205, v217
	v_fmac_f32_e32 v146, v206, v218
	v_fmac_f32_e32 v147, v207, v219
	v_mul_f32_e32 v212, v145, v145
	v_fmac_f32_e32 v212, v144, v144
	v_fmac_f32_e32 v212, v146, v146
	v_fmac_f32_e32 v212, v147, v147
	v_add_f32_e32 v77, v77, v212
	ds_read_b128 v[204:207], v71 offset:5120
	ds_read_b128 v[208:211], v71 offset:37888
	v_lshlrev_b32_e32 v212, 16, v50
	v_and_b32_e32 v213, 0xffff0000, v50
	v_lshlrev_b32_e32 v214, 16, v51
	v_and_b32_e32 v215, 0xffff0000, v51
	v_lshlrev_b32_e32 v216, 16, v44
	v_and_b32_e32 v217, 0xffff0000, v44
	v_lshlrev_b32_e32 v218, 16, v45
	v_and_b32_e32 v219, 0xffff0000, v45
	v_mul_f32_e32 v212, v68, v212
	v_mul_f32_e32 v213, v68, v213
	v_mul_f32_e32 v214, v68, v214
	v_mul_f32_e32 v215, v68, v215
	v_mul_f32_e32 v216, v69, v216
	v_mul_f32_e32 v217, v69, v217
	v_mul_f32_e32 v218, v69, v218
	v_mul_f32_e32 v219, v69, v219
	s_waitcnt lgkmcnt(2)
	v_mul_f32_e32 v148, v212, v200
	v_mul_f32_e32 v149, v213, v201
	v_mul_f32_e32 v150, v214, v202
	v_mul_f32_e32 v151, v215, v203
	v_fmac_f32_e32 v148, v196, v216
	v_fmac_f32_e32 v149, v197, v217
	v_fmac_f32_e32 v150, v198, v218
	v_fmac_f32_e32 v151, v199, v219
	v_mul_f32_e32 v212, v149, v149
	v_fmac_f32_e32 v212, v148, v148
	v_fmac_f32_e32 v212, v150, v150
	v_fmac_f32_e32 v212, v151, v151
	v_add_f32_e32 v77, v77, v212
	ds_read_b128 v[196:199], v71 offset:6144
	ds_read_b128 v[200:203], v71 offset:38912
	v_lshlrev_b32_e32 v212, 16, v46
	v_and_b32_e32 v213, 0xffff0000, v46
	v_lshlrev_b32_e32 v214, 16, v47
	v_and_b32_e32 v215, 0xffff0000, v47
	v_lshlrev_b32_e32 v216, 16, v42
	v_and_b32_e32 v217, 0xffff0000, v42
	v_lshlrev_b32_e32 v218, 16, v43
	v_and_b32_e32 v219, 0xffff0000, v43
	v_mul_f32_e32 v212, v68, v212
	v_mul_f32_e32 v213, v68, v213
	v_mul_f32_e32 v214, v68, v214
	v_mul_f32_e32 v215, v68, v215
	v_mul_f32_e32 v216, v69, v216
	v_mul_f32_e32 v217, v69, v217
	v_mul_f32_e32 v218, v69, v218
	v_mul_f32_e32 v219, v69, v219
	s_waitcnt lgkmcnt(2)
; #define LAS __attribute__((address_space(3)))
; __device__ __forceinline__ float bflo(unsigned w) { return __uint_as_float(w << 16); }
; __device__ __forceinline__ float bfhi(unsigned w) { return __uint_as_float(w & 0xffff0000u); }
; template <int MODE> ...
;     ...
;             for (int j = 0; j < 16; ++j) { const f32x4 g = *(const LAS f32x4*)(GP + lo4 + 256 * j), gi = *(const LAS f32x4*)(GI + lo4 + 256 * j);
;                 f32x4 x;
;                 x.x = bflo(pw[j].x) * ri * gi.x + bflo(hw[j].x) * rstd * g.x; x.y = bfhi(pw[j].x) * ri * gi.y + bfhi(hw[j].x) * rstd * g.y;
;                 x.z = bflo(pw[j].y) * ri * gi.z + bflo(hw[j].y) * rstd * g.z; x.w = bfhi(pw[j].y) * ri * gi.w + bfhi(hw[j].y) * rstd * g.w;
;                 if (MODE == 2) *(f32x4*)(xout + (size_t)row * DM + lo4 + 256 * j) = x;
;                 else ss2 += x.x * x.x + x.y * x.y + x.z * x.z + x.w * x.w;
;                 if (j & 1) __builtin_amdgcn_sched_barrier(0); }
	v_mul_f32_e32 v152, v212, v208
	v_mul_f32_e32 v153, v213, v209
	v_mul_f32_e32 v154, v214, v210
	v_mul_f32_e32 v155, v215, v211
	v_fmac_f32_e32 v152, v204, v216
	v_fmac_f32_e32 v153, v205, v217
	v_fmac_f32_e32 v154, v206, v218
	v_fmac_f32_e32 v155, v207, v219
	v_mul_f32_e32 v212, v153, v153
	v_fmac_f32_e32 v212, v152, v152
	v_fmac_f32_e32 v212, v154, v154
	v_fmac_f32_e32 v212, v155, v155
	v_add_f32_e32 v77, v77, v212
	ds_read_b128 v[204:207], v71 offset:7168
	ds_read_b128 v[208:211], v71 offset:39936
	v_lshlrev_b32_e32 v212, 16, v40
	v_and_b32_e32 v213, 0xffff0000, v40
	v_lshlrev_b32_e32 v214, 16, v41
	v_and_b32_e32 v215, 0xffff0000, v41
	v_lshlrev_b32_e32 v216, 16, v38
	v_and_b32_e32 v217, 0xffff0000, v38
	v_lshlrev_b32_e32 v218, 16, v39
	v_and_b32_e32 v219, 0xffff0000, v39
	v_mul_f32_e32 v212, v68, v212
	v_mul_f32_e32 v213, v68, v213
	v_mul_f32_e32 v214, v68, v214
	v_mul_f32_e32 v215, v68, v215
	v_mul_f32_e32 v216, v69, v216
	v_mul_f32_e32 v217, v69, v217
	v_mul_f32_e32 v218, v69, v218
	v_mul_f32_e32 v219, v69, v219
	s_waitcnt lgkmcnt(2)
	v_mul_f32_e32 v156, v212, v200
	v_mul_f32_e32 v157, v213, v201
	v_mul_f32_e32 v158, v214, v202
	v_mul_f32_e32 v159, v215, v203
	v_fmac_f32_e32 v156, v196, v216
	v_fmac_f32_e32 v157, v197, v217
	v_fmac_f32_e32 v158, v198, v218
	v_fmac_f32_e32 v159, v199, v219
	v_mul_f32_e32 v212, v157, v157
	v_fmac_f32_e32 v212, v156, v156
	v_fmac_f32_e32 v212, v158, v158
	v_fmac_f32_e32 v212, v159, v159
	v_add_f32_e32 v77, v77, v212
	ds_read_b128 v[196:199], v71 offset:8192
	ds_read_b128 v[200:203], v71 offset:40960
	v_lshlrev_b32_e32 v212, 16, v36
	v_and_b32_e32 v213, 0xffff0000, v36
	v_lshlrev_b32_e32 v214, 16, v37
	v_and_b32_e32 v215, 0xffff0000, v37
	v_lshlrev_b32_e32 v216, 16, v34
	v_and_b32_e32 v217, 0xffff0000, v34
	v_lshlrev_b32_e32 v218, 16, v35
	v_and_b32_e32 v219, 0xffff0000, v35
	v_mul_f32_e32 v212, v68, v212
	v_mul_f32_e32 v213, v68, v213
	v_mul_f32_e32 v214, v68, v214
	v_mul_f32_e32 v215, v68, v215
	v_mul_f32_e32 v216, v69, v216
	v_mul_f32_e32 v217, v69, v217
	v_mul_f32_e32 v218, v69, v218
	v_mul_f32_e32 v219, v69, v219
	s_waitcnt lgkmcnt(2)
	v_mul_f32_e32 v160, v212, v208
	v_mul_f32_e32 v161, v213, v209
	v_mul_f32_e32 v162, v214, v210
	v_mul_f32_e32 v163, v215, v211
	v_fmac_f32_e32 v160, v204, v216
	v_fmac_f32_e32 v161, v205, v217
	v_fmac_f32_e32 v162, v206, v218
	v_fmac_f32_e32 v163, v207, v219
	v_mul_f32_e32 v212, v161, v161
	v_fmac_f32_e32 v212, v160, v160
	v_fmac_f32_e32 v212, v162, v162
	v_fmac_f32_e32 v212, v163, v163
	v_add_f32_e32 v77, v77, v212
	ds_read_b128 v[204:207], v71 offset:9216
	ds_read_b128 v[208:211], v71 offset:41984
	v_lshlrev_b32_e32 v212, 16, v30
	v_and_b32_e32 v213, 0xffff0000, v30
	v_lshlrev_b32_e32 v214, 16, v31
	v_and_b32_e32 v215, 0xffff0000, v31
	v_lshlrev_b32_e32 v216, 16, v32
	v_and_b32_e32 v217, 0xffff0000, v32
	v_lshlrev_b32_e32 v218, 16, v33
	v_and_b32_e32 v219, 0xffff0000, v33
	v_mul_f32_e32 v212, v68, v212
	v_mul_f32_e32 v213, v68, v213
	v_mul_f32_e32 v214, v68, v214
	v_mul_f32_e32 v215, v68, v215
	v_mul_f32_e32 v216, v69, v216
	v_mul_f32_e32 v217, v69, v217
	v_mul_f32_e32 v218, v69, v218
	v_mul_f32_e32 v219, v69, v219
	s_waitcnt lgkmcnt(2)
	v_mul_f32_e32 v164, v212, v200
	v_mul_f32_e32 v165, v213, v201
	v_mul_f32_e32 v166, v214, v202
	v_mul_f32_e32 v167, v215, v203
	v_fmac_f32_e32 v164, v196, v216
	v_fmac_f32_e32 v165, v197, v217
	v_fmac_f32_e32 v166, v198, v218
	v_fmac_f32_e32 v167, v199, v219
	v_mul_f32_e32 v212, v165, v165
	v_fmac_f32_e32 v212, v164, v164
	v_fmac_f32_e32 v212, v166, v166
	v_fmac_f32_e32 v212, v167, v167
	v_add_f32_e32 v77, v77, v212
	ds_read_b128 v[196:199], v71 offset:10240
	ds_read_b128 v[200:203], v71 offset:43008
	v_lshlrev_b32_e32 v212, 16, v26
	v_and_b32_e32 v213, 0xffff0000, v26
	v_lshlrev_b32_e32 v214, 16, v27
	v_and_b32_e32 v215, 0xffff0000, v27
	v_lshlrev_b32_e32 v216, 16, v28
	v_and_b32_e32 v217, 0xffff0000, v28
	v_lshlrev_b32_e32 v218, 16, v29
	v_and_b32_e32 v219, 0xffff0000, v29
	v_mul_f32_e32 v212, v68, v212
	v_mul_f32_e32 v213, v68, v213
	v_mul_f32_e32 v214, v68, v214
	v_mul_f32_e32 v215, v68, v215
	v_mul_f32_e32 v216, v69, v216
	v_mul_f32_e32 v217, v69, v217
	v_mul_f32_e32 v218, v69, v218
	v_mul_f32_e32 v219, v69, v219
	s_waitcnt lgkmcnt(2)
	v_mul_f32_e32 v168, v212, v208
	v_mul_f32_e32 v169, v213, v209
	v_mul_f32_e32 v170, v214, v210
	v_mul_f32_e32 v171, v215, v211
	v_fmac_f32_e32 v168, v204, v216
	v_fmac_f32_e32 v169, v205, v217
	v_fmac_f32_e32 v170, v206, v218
	v_fmac_f32_e32 v171, v207, v219
	v_mul_f32_e32 v212, v169, v169
	v_fmac_f32_e32 v212, v168, v168
	v_fmac_f32_e32 v212, v170, v170
	v_fmac_f32_e32 v212, v171, v171
	v_add_f32_e32 v77, v77, v212
	ds_read_b128 v[204:207], v71 offset:11264
	ds_read_b128 v[208:211], v71 offset:44032
	v_lshlrev_b32_e32 v212, 16, v22
	v_and_b32_e32 v213, 0xffff0000, v22
	v_lshlrev_b32_e32 v214, 16, v23
	v_and_b32_e32 v215, 0xffff0000, v23
	v_lshlrev_b32_e32 v216, 16, v24
	v_and_b32_e32 v217, 0xffff0000, v24
	v_lshlrev_b32_e32 v218, 16, v25
	v_and_b32_e32 v219, 0xffff0000, v25
	v_mul_f32_e32 v212, v68, v212
	v_mul_f32_e32 v213, v68, v213
	v_mul_f32_e32 v214, v68, v214
	v_mul_f32_e32 v215, v68, v215
	v_mul_f32_e32 v216, v69, v216
	v_mul_f32_e32 v217, v69, v217
	v_mul_f32_e32 v218, v69, v218
	v_mul_f32_e32 v219, v69, v219
	s_waitcnt lgkmcnt(2)
; #define LAS __attribute__((address_space(3)))
; __device__ __forceinline__ float bflo(unsigned w) { return __uint_as_float(w << 16); }
; __device__ __forceinline__ float bfhi(unsigned w) { return __uint_as_float(w & 0xffff0000u); }
; template <int MODE> ...
;     ...
;             for (int j = 0; j < 16; ++j) { const f32x4 g = *(const LAS f32x4*)(GP + lo4 + 256 * j), gi = *(const LAS f32x4*)(GI + lo4 + 256 * j);
;                 f32x4 x;
;                 x.x = bflo(pw[j].x) * ri * gi.x + bflo(hw[j].x) * rstd * g.x; x.y = bfhi(pw[j].x) * ri * gi.y + bfhi(hw[j].x) * rstd * g.y;
;                 x.z = bflo(pw[j].y) * ri * gi.z + bflo(hw[j].y) * rstd * g.z; x.w = bfhi(pw[j].y) * ri * gi.w + bfhi(hw[j].y) * rstd * g.w;
;                 if (MODE == 2) *(f32x4*)(xout + (size_t)row * DM + lo4 + 256 * j) = x;
;                 else ss2 += x.x * x.x + x.y * x.y + x.z * x.z + x.w * x.w;
;                 if (j & 1) __builtin_amdgcn_sched_barrier(0); }
;             if (MODE == 1) {
;                 const float rstd2 = rsqrtf(wave_sum(ss2) * (1.f / DM) + EPS);
;                 if (lane == 0) rs_out[row] = rstd2;
	v_mul_f32_e32 v172, v212, v200
	v_mul_f32_e32 v173, v213, v201
	v_mul_f32_e32 v174, v214, v202
	v_mul_f32_e32 v175, v215, v203
	v_fmac_f32_e32 v172, v196, v216
	v_fmac_f32_e32 v173, v197, v217
	v_fmac_f32_e32 v174, v198, v218
	v_fmac_f32_e32 v175, v199, v219
	v_mul_f32_e32 v212, v173, v173
	v_fmac_f32_e32 v212, v172, v172
	v_fmac_f32_e32 v212, v174, v174
	v_fmac_f32_e32 v212, v175, v175
	v_add_f32_e32 v77, v77, v212
	ds_read_b128 v[196:199], v71 offset:12288
	ds_read_b128 v[200:203], v71 offset:45056
	v_lshlrev_b32_e32 v212, 16, v18
	v_and_b32_e32 v213, 0xffff0000, v18
	v_lshlrev_b32_e32 v214, 16, v19
	v_and_b32_e32 v215, 0xffff0000, v19
	v_lshlrev_b32_e32 v216, 16, v20
	v_and_b32_e32 v217, 0xffff0000, v20
	v_lshlrev_b32_e32 v218, 16, v21
	v_and_b32_e32 v219, 0xffff0000, v21
	v_mul_f32_e32 v212, v68, v212
	v_mul_f32_e32 v213, v68, v213
	v_mul_f32_e32 v214, v68, v214
	v_mul_f32_e32 v215, v68, v215
	v_mul_f32_e32 v216, v69, v216
	v_mul_f32_e32 v217, v69, v217
	v_mul_f32_e32 v218, v69, v218
	v_mul_f32_e32 v219, v69, v219
	s_waitcnt lgkmcnt(2)
	v_mul_f32_e32 v176, v212, v208
	v_mul_f32_e32 v177, v213, v209
	v_mul_f32_e32 v178, v214, v210
	v_mul_f32_e32 v179, v215, v211
	v_fmac_f32_e32 v176, v204, v216
	v_fmac_f32_e32 v177, v205, v217
	v_fmac_f32_e32 v178, v206, v218
	v_fmac_f32_e32 v179, v207, v219
	v_mul_f32_e32 v212, v177, v177
	v_fmac_f32_e32 v212, v176, v176
	v_fmac_f32_e32 v212, v178, v178
	v_fmac_f32_e32 v212, v179, v179
	v_add_f32_e32 v77, v77, v212
	ds_read_b128 v[204:207], v71 offset:13312
	ds_read_b128 v[208:211], v71 offset:46080
	v_lshlrev_b32_e32 v212, 16, v14
	v_and_b32_e32 v213, 0xffff0000, v14
	v_lshlrev_b32_e32 v214, 16, v15
	v_and_b32_e32 v215, 0xffff0000, v15
	v_lshlrev_b32_e32 v216, 16, v16
	v_and_b32_e32 v217, 0xffff0000, v16
	v_lshlrev_b32_e32 v218, 16, v17
	v_and_b32_e32 v219, 0xffff0000, v17
	v_mul_f32_e32 v212, v68, v212
	v_mul_f32_e32 v213, v68, v213
	v_mul_f32_e32 v214, v68, v214
	v_mul_f32_e32 v215, v68, v215
	v_mul_f32_e32 v216, v69, v216
	v_mul_f32_e32 v217, v69, v217
	v_mul_f32_e32 v218, v69, v218
	v_mul_f32_e32 v219, v69, v219
	s_waitcnt lgkmcnt(2)
	v_mul_f32_e32 v180, v212, v200
	v_mul_f32_e32 v181, v213, v201
	v_mul_f32_e32 v182, v214, v202
	v_mul_f32_e32 v183, v215, v203
	v_fmac_f32_e32 v180, v196, v216
	v_fmac_f32_e32 v181, v197, v217
	v_fmac_f32_e32 v182, v198, v218
	v_fmac_f32_e32 v183, v199, v219
	v_mul_f32_e32 v212, v181, v181
	v_fmac_f32_e32 v212, v180, v180
	v_fmac_f32_e32 v212, v182, v182
	v_fmac_f32_e32 v212, v183, v183
	v_add_f32_e32 v77, v77, v212
	ds_read_b128 v[196:199], v71 offset:14336
	ds_read_b128 v[200:203], v71 offset:47104
	v_lshlrev_b32_e32 v212, 16, v10
	v_and_b32_e32 v213, 0xffff0000, v10
	v_lshlrev_b32_e32 v214, 16, v11
	v_and_b32_e32 v215, 0xffff0000, v11
	v_lshlrev_b32_e32 v216, 16, v12
	v_and_b32_e32 v217, 0xffff0000, v12
	v_lshlrev_b32_e32 v218, 16, v13
	v_and_b32_e32 v219, 0xffff0000, v13
	v_mul_f32_e32 v212, v68, v212
	v_mul_f32_e32 v213, v68, v213
	v_mul_f32_e32 v214, v68, v214
	v_mul_f32_e32 v215, v68, v215
	v_mul_f32_e32 v216, v69, v216
	v_mul_f32_e32 v217, v69, v217
	v_mul_f32_e32 v218, v69, v218
	v_mul_f32_e32 v219, v69, v219
	s_waitcnt lgkmcnt(2)
	v_mul_f32_e32 v184, v212, v208
	v_mul_f32_e32 v185, v213, v209
	v_mul_f32_e32 v186, v214, v210
	v_mul_f32_e32 v187, v215, v211
	v_fmac_f32_e32 v184, v204, v216
	v_fmac_f32_e32 v185, v205, v217
	v_fmac_f32_e32 v186, v206, v218
	v_fmac_f32_e32 v187, v207, v219
	v_mul_f32_e32 v212, v185, v185
	v_fmac_f32_e32 v212, v184, v184
	v_fmac_f32_e32 v212, v186, v186
	v_fmac_f32_e32 v212, v187, v187
	v_add_f32_e32 v77, v77, v212
	ds_read_b128 v[204:207], v71 offset:15360
	ds_read_b128 v[208:211], v71 offset:48128
	v_lshlrev_b32_e32 v212, 16, v6
	v_and_b32_e32 v213, 0xffff0000, v6
	v_lshlrev_b32_e32 v214, 16, v7
	v_and_b32_e32 v215, 0xffff0000, v7
	v_lshlrev_b32_e32 v216, 16, v8
	v_and_b32_e32 v217, 0xffff0000, v8
	v_lshlrev_b32_e32 v218, 16, v9
	v_and_b32_e32 v219, 0xffff0000, v9
	v_mul_f32_e32 v212, v68, v212
	v_mul_f32_e32 v213, v68, v213
	v_mul_f32_e32 v214, v68, v214
	v_mul_f32_e32 v215, v68, v215
	v_mul_f32_e32 v216, v69, v216
	v_mul_f32_e32 v217, v69, v217
	v_mul_f32_e32 v218, v69, v218
	v_mul_f32_e32 v219, v69, v219
	s_waitcnt lgkmcnt(2)
	v_mul_f32_e32 v188, v212, v200
	v_mul_f32_e32 v189, v213, v201
	v_mul_f32_e32 v190, v214, v202
	v_mul_f32_e32 v191, v215, v203
	v_fmac_f32_e32 v188, v196, v216
	v_fmac_f32_e32 v189, v197, v217
	v_fmac_f32_e32 v190, v198, v218
	v_fmac_f32_e32 v191, v199, v219
	v_mul_f32_e32 v212, v189, v189
	v_fmac_f32_e32 v212, v188, v188
	v_fmac_f32_e32 v212, v190, v190
	v_fmac_f32_e32 v212, v191, v191
	v_add_f32_e32 v77, v77, v212
	v_lshlrev_b32_e32 v212, 16, v2
	v_and_b32_e32 v213, 0xffff0000, v2
	v_lshlrev_b32_e32 v214, 16, v3
	v_and_b32_e32 v215, 0xffff0000, v3
	v_lshlrev_b32_e32 v216, 16, v4
	v_and_b32_e32 v217, 0xffff0000, v4
	v_lshlrev_b32_e32 v218, 16, v5
	v_and_b32_e32 v219, 0xffff0000, v5
	v_mul_f32_e32 v212, v68, v212
	v_mul_f32_e32 v213, v68, v213
	v_mul_f32_e32 v214, v68, v214
	v_mul_f32_e32 v215, v68, v215
	v_mul_f32_e32 v216, v69, v216
	v_mul_f32_e32 v217, v69, v217
	v_mul_f32_e32 v218, v69, v218
	v_mul_f32_e32 v219, v69, v219
	s_waitcnt lgkmcnt(0)
	v_mul_f32_e32 v192, v212, v208
	v_mul_f32_e32 v193, v213, v209
	v_mul_f32_e32 v194, v214, v210
	v_mul_f32_e32 v195, v215, v211
	v_fmac_f32_e32 v192, v204, v216
	v_fmac_f32_e32 v193, v205, v217
	v_fmac_f32_e32 v194, v206, v218
	v_fmac_f32_e32 v195, v207, v219
	v_mul_f32_e32 v212, v193, v193
	v_fmac_f32_e32 v212, v192, v192
	v_fmac_f32_e32 v212, v194, v194
	v_fmac_f32_e32 v212, v195, v195
	v_add_f32_e32 v77, v77, v212
	ds_bpermute_b32 v70, v70, v77
	s_waitcnt lgkmcnt(0)
	v_add_f32_e32 v70, v77, v70
	ds_bpermute_b32 v72, v72, v70
	s_waitcnt lgkmcnt(0)
	v_add_f32_e32 v70, v70, v72
	ds_bpermute_b32 v72, v73, v70
	s_waitcnt lgkmcnt(0)
	v_add_f32_e32 v70, v70, v72
	ds_bpermute_b32 v72, v74, v70
	s_waitcnt lgkmcnt(0)
	v_add_f32_e32 v70, v70, v72
	ds_bpermute_b32 v72, v75, v70
	s_waitcnt lgkmcnt(0)
	v_add_f32_e32 v70, v70, v72
	ds_bpermute_b32 v72, v76, v70
	s_waitcnt lgkmcnt(0)
	v_add_f32_e32 v70, v70, v72
	v_fmamk_f32 v70, v70, 0x39800000, v99
	v_mul_f32_e32 v72, 0x4b800000, v70
	v_cmp_gt_f32_e32 vcc, s66, v70
	s_nop 1
	v_cndmask_b32_e32 v70, v70, v72, vcc
	v_rsq_f32_e32 v70, v70
	s_nop 0
	v_mul_f32_e32 v72, 0x45800000, v70
	v_cndmask_b32_e32 v70, v70, v72, vcc
	s_and_saveexec_b64 s[6:7], s[4:5]
	s_cbranch_execz .LBB0_775
	global_store_dword v98, v70, s[62:63]
	s_branch .LBB0_775

; #define LAS __attribute__((address_space(3)))
; template <int MODE> ...
;     ...
;     __syncthreads();
; #pragma unroll
;     for (int i = 0; i < 2; ++i) { const int o = 4 * (tid + NTHREADS * i);
;         if (MODE != 0) { *(LAS f32x4*)(GP + o) = *(const f32x4*)(gpost + o); const f32x4 g = *(const f32x4*)(gprev + o); *(LAS f32x4*)(GI + o) = (f32x4){1.f / g.x, 1.f / g.y, 1.f / g.z, 1.f / g.w}; }
;         if (MODE != 2) *(LAS f32x4*)(GN + o) = *(const f32x4*)(gpre + o); }
;     __syncthreads();
;     const int lo4 = 4 * lane;
; #pragma unroll 1
;     for (int row = gw; row < SEQ; row += NGW) {
.LBB0_1115:
	s_cmp_gt_i32 s36, 10
	s_cselect_b64 s[6:7], -1, 0
	s_xor_b64 s[4:5], s[4:5], -1
	s_or_b64 s[4:5], s[6:7], s[4:5]
	s_and_b64 vcc, exec, s[4:5]
	s_cbranch_vccnz .LBB0_1121
	s_mov_b64 s[12:13], 0
	s_waitcnt vmcnt(0)
	v_mbcnt_lo_u32_b32 v2, -1, 0
	v_mbcnt_hi_u32_b32 v2, -1, v2
	s_load_dwordx4 s[4:7], s[0:1], 0x70
	s_load_dwordx2 s[8:9], s[0:1], 0xa8
	v_lshlrev_b32_e32 v0, 2, v2
	v_lshl_add_u32 v24, s89, 8, v0
	v_ashrrev_i32_e32 v25, 31, v24
	v_lshlrev_b64 v[12:13], 2, v[24:25]
	v_add_u32_e32 v16, 0x800, v24
	s_waitcnt lgkmcnt(0)
	v_lshl_add_u64 v[8:9], s[4:5], 0, v[12:13]
	v_ashrrev_i32_e32 v17, 31, v16
	s_barrier
	v_lshl_add_u64 v[4:5], s[6:7], 0, v[12:13]
	global_load_dwordx4 v[8:11], v[8:9], off
	v_lshl_add_u64 v[12:13], s[8:9], 0, v[12:13]
	v_lshlrev_b64 v[26:27], 2, v[16:17]
	global_load_dwordx4 v[4:7], v[4:5], off
	v_lshl_add_u64 v[16:17], s[6:7], 0, v[26:27]
	global_load_dwordx4 v[12:15], v[12:13], off
	v_lshl_add_u64 v[20:21], s[4:5], 0, v[26:27]
	global_load_dwordx4 v[16:19], v[16:17], off
	v_lshl_add_u32 v1, v24, 2, 0
	global_load_dwordx4 v[20:23], v[20:21], off
	v_lshl_add_u64 v[24:25], s[8:9], 0, v[26:27]
	global_load_dwordx4 v[24:27], v[24:25], off
	s_cmpk_gt_i32 s40, 0x1fff
	s_waitcnt vmcnt(5)
	v_div_scale_f32 v3, s[4:5], v8, v8, 1.0
	v_div_scale_f32 v29, s[8:9], v11, v11, 1.0
	s_waitcnt vmcnt(4)
	ds_write_b128 v1, v[4:7]
	v_div_scale_f32 v5, s[4:5], v9, v9, 1.0
	s_waitcnt vmcnt(3)
	ds_write_b128 v1, v[12:15] offset:16384
	v_rcp_f32_e32 v12, v3
	v_div_scale_f32 v7, s[6:7], v10, v10, 1.0
	v_rcp_f32_e32 v13, v5
	s_waitcnt vmcnt(2)
	ds_write_b128 v1, v[16:19] offset:8192
	s_waitcnt vmcnt(1)
	v_div_scale_f32 v16, s[10:11], v20, v20, 1.0
	v_rcp_f32_e32 v14, v7
	v_rcp_f32_e32 v19, v16
	v_rcp_f32_e32 v15, v29
	v_fma_f32 v32, -v3, v12, 1.0
	v_div_scale_f32 v4, vcc, 1.0, v8, 1.0
	v_fma_f32 v33, -v5, v13, 1.0
	v_fmac_f32_e32 v12, v32, v12
	v_div_scale_f32 v6, s[4:5], 1.0, v9, 1.0
	v_fma_f32 v34, -v7, v14, 1.0
	v_fmac_f32_e32 v13, v33, v13
	v_fma_f32 v32, -v16, v19, 1.0
	v_mul_f32_e32 v33, v4, v12
	v_div_scale_f32 v28, s[6:7], 1.0, v10, 1.0
	v_fma_f32 v35, -v29, v15, 1.0
	v_fmac_f32_e32 v14, v34, v14
	v_mul_f32_e32 v34, v6, v13
	v_fmac_f32_e32 v19, v32, v19
	v_fma_f32 v32, -v3, v33, v4
	v_div_scale_f32 v30, s[8:9], 1.0, v11, 1.0
	v_fmac_f32_e32 v15, v35, v15
	v_mul_f32_e32 v35, v28, v14
	v_fma_f32 v37, -v5, v34, v6
	v_fmac_f32_e32 v33, v32, v12
	v_div_scale_f32 v17, s[10:11], 1.0, v20, 1.0
	v_mul_f32_e32 v36, v30, v15
	v_fma_f32 v38, -v7, v35, v28
	v_fmac_f32_e32 v34, v37, v13
	v_fma_f32 v3, -v3, v33, v4
	v_div_scale_f32 v18, s[14:15], v21, v21, 1.0
	v_fma_f32 v39, -v29, v36, v30
	v_mul_f32_e32 v40, v17, v19
	v_fmac_f32_e32 v35, v38, v14
	v_fma_f32 v5, -v5, v34, v6
	v_div_fmas_f32 v3, v3, v12, v33
	s_mov_b64 vcc, s[4:5]
	v_rcp_f32_e32 v31, v18
	v_fmac_f32_e32 v36, v39, v15
	v_fma_f32 v32, -v16, v40, v17
	v_fma_f32 v6, -v7, v35, v28
	v_div_fixup_f32 v4, v3, v8, 1.0
	v_div_fmas_f32 v3, v5, v13, v34
	s_mov_b64 vcc, s[6:7]
	v_fma_f32 v7, -v29, v36, v30
	v_fmac_f32_e32 v40, v32, v19
	v_div_fixup_f32 v5, v3, v9, 1.0
	v_div_fmas_f32 v3, v6, v14, v35
	s_mov_b64 vcc, s[8:9]
	v_fma_f32 v12, -v16, v40, v17
	v_div_fixup_f32 v6, v3, v10, 1.0
	v_div_fmas_f32 v3, v7, v15, v36
	s_mov_b64 vcc, s[10:11]
	v_div_fixup_f32 v7, v3, v11, 1.0
	v_div_fmas_f32 v3, v12, v19, v40
	ds_write_b128 v1, v[4:7] offset:32768
	v_div_fixup_f32 v4, v3, v20, 1.0
	v_fma_f32 v3, -v18, v31, 1.0
	v_fmac_f32_e32 v31, v3, v31
	v_div_scale_f32 v3, vcc, 1.0, v21, 1.0
	v_mul_f32_e32 v5, v3, v31
	v_fma_f32 v6, -v18, v5, v3
	v_fmac_f32_e32 v5, v6, v31
	v_div_scale_f32 v6, s[4:5], v22, v22, 1.0
	v_rcp_f32_e32 v7, v6
	v_fma_f32 v3, -v18, v5, v3
	v_div_fmas_f32 v3, v3, v31, v5
	v_div_fixup_f32 v5, v3, v21, 1.0
	v_fma_f32 v3, -v6, v7, 1.0
	v_fmac_f32_e32 v7, v3, v7
	v_div_scale_f32 v3, vcc, 1.0, v22, 1.0
	v_mul_f32_e32 v8, v3, v7
	v_fma_f32 v9, -v6, v8, v3
	v_fmac_f32_e32 v8, v9, v7
	v_div_scale_f32 v9, s[4:5], v23, v23, 1.0
	v_rcp_f32_e32 v10, v9
	v_fma_f32 v3, -v6, v8, v3
	v_div_fmas_f32 v3, v3, v7, v8
	v_div_fixup_f32 v6, v3, v22, 1.0
	v_fma_f32 v3, -v9, v10, 1.0
	v_fmac_f32_e32 v10, v3, v10
	v_div_scale_f32 v3, vcc, 1.0, v23, 1.0
	v_mul_f32_e32 v7, v3, v10
	v_fma_f32 v8, -v9, v7, v3
	v_fmac_f32_e32 v7, v8, v10
	v_fma_f32 v3, -v9, v7, v3
	v_div_fmas_f32 v3, v3, v10, v7
	v_div_fixup_f32 v7, v3, v23, 1.0
	ds_write_b128 v1, v[4:7] offset:40960
	s_waitcnt vmcnt(0)
	ds_write_b128 v1, v[24:27] offset:24576
	s_waitcnt lgkmcnt(0)
	s_barrier
	s_cbranch_scc1 .LBB0_1121
	s_load_dwordx2 s[6:7], s[0:1], 0xe8
	s_ashr_i32 s41, s40, 31
	s_lshl_b64 s[8:9], s[40:41], 2
	v_ashrrev_i32_e32 v1, 31, v0
	v_cmp_eq_u32_e64 s[4:5], 0, v2
	s_waitcnt lgkmcnt(0)
	s_add_u32 s8, s6, s8
	s_addc_u32 s9, s7, s9
	s_add_u32 s64, s8, 0x2c0000
	s_addc_u32 s65, s9, 0
	s_ashr_i32 s39, s38, 31
	s_lshl_b64 s[8:9], s[38:39], 2
	s_lshl_b64 s[10:11], s[40:41], 13
	s_add_u32 s6, s6, s10
	s_addc_u32 s7, s7, s11
	v_mbcnt_lo_u32_b32 v2, -1, 0
	v_lshl_add_u32 v71, v0, 2, 0
	v_lshl_add_u64 v[0:1], v[0:1], 1, s[6:7]
	s_lshl_b64 s[10:11], s[38:39], 13
	s_mov_b64 s[14:15], 0x3000000
	s_mov_b64 s[18:19], 0x3000200
	s_mov_b64 s[20:21], 0x3000400
	s_mov_b64 s[22:23], 0x3000600
	s_mov_b64 s[24:25], 0x3000800
	s_mov_b64 s[26:27], 0x3000a00
	s_mov_b64 s[42:43], 0x3000c00
	s_mov_b64 s[44:45], 0x3000e00
	s_mov_b64 s[46:47], 0x3001000
	s_mov_b32 s39, 0x3001000
	s_mov_b32 s41, 0x7001000
	s_mov_b64 s[48:49], 0x3001200
	s_mov_b64 s[50:51], 0x3001400
	s_mov_b64 s[52:53], 0x3001600
	s_mov_b64 s[54:55], 0x3001800
	s_mov_b64 s[56:57], 0x3001a00
	s_mov_b64 s[58:59], 0x3001c00
	s_mov_b64 s[60:61], 0x3001e00
	v_mov_b32_e32 v79, 0
	v_mov_b32_e32 v100, 0x358637bd
	s_mov_b32 s66, 0x800000
	v_mbcnt_hi_u32_b32 v101, -1, v2
	s_mov_b32 s67, s40
	s_mov_b32 s96, 0x3000000
	s_mov_b32 s97, 0x3001000
	s_branch .LBB0_1119
; #define LAS __attribute__((address_space(3)))
; __device__ __forceinline__ unsigned pk2(float lo, float hi) { const f32x2c v = {lo, hi}; return __builtin_bit_cast(unsigned, __builtin_convertvector(v, bf16x2c)); }
; __device__ __forceinline__ float bflo(unsigned w) { return __uint_as_float(w << 16); }
; __device__ __forceinline__ float bfhi(unsigned w) { return __uint_as_float(w & 0xffff0000u); }
; #define LAUNDER_ROW(pw, hw) do { LAUNDER8(pw, 0); LAUNDER8(pw, 8); LAUNDER8(hw, 0); LAUNDER8(hw, 8); } while (0)
; template <int MODE> ...
;     ...
;                 LAUNDER_ROW(pw, hw);
;                 float ri2 = ri, rstdb = rstd; asm volatile("" : "+v"(ri2), "+v"(rstdb) :: "memory");
; #pragma unroll
;                 for (int j = 0; j < 16; ++j) { const f32x4 g = *(const LAS f32x4*)(GP + lo4 + 256 * j), gi = *(const LAS f32x4*)(GI + lo4 + 256 * j), gn = *(const LAS f32x4*)(GN + lo4 + 256 * j);
;                     f32x4 x;
;                     x.x = bflo(pw[j].x) * ri2 * gi.x + bflo(hw[j].x) * rstdb * g.x; x.y = bfhi(pw[j].x) * ri2 * gi.y + bfhi(hw[j].x) * rstdb * g.y;
;                     x.z = bflo(pw[j].y) * ri2 * gi.z + bflo(hw[j].y) * rstdb * g.z; x.w = bfhi(pw[j].y) * ri2 * gi.w + bfhi(hw[j].y) * rstdb * g.w;
;                     v2u w; w.x = pk2(x.x * rstd2 * gn.x, x.y * rstd2 * gn.y); w.y = pk2(x.z * rstd2 * gn.z, x.w * rstd2 * gn.w);
;                     *(v2u*)(pw_out + lo4 + 256 * j) = w;
;                     if (j & 1) __builtin_amdgcn_sched_barrier(0); }
.LBB0_1118:
	s_or_b64 exec, exec, s[6:7]
	v_mov_b32_e32 v78, v27
	v_add_co_u32_e32 v224, vcc, s96, v68
	s_nop 1
	v_addc_co_u32_e32 v225, vcc, 0, v69, vcc
	v_add_co_u32_e32 v226, vcc, s97, v68
	s_nop 1
	v_addc_co_u32_e32 v227, vcc, 0, v69, vcc
	ds_read_b128 v[196:199], v71 offset:16384
	ds_read_b128 v[204:207], v71 offset:17408
	v_mul_f32_e32 v212, v70, v132
	v_mul_f32_e32 v213, v70, v133
	v_mul_f32_e32 v214, v70, v134
	v_mul_f32_e32 v215, v70, v135
	s_waitcnt lgkmcnt(1)
	v_mul_f32_e32 v212, v196, v212
	v_mul_f32_e32 v213, v197, v213
	v_mul_f32_e32 v214, v198, v214
	v_mul_f32_e32 v215, v199, v215
	v_cvt_pk_bf16_f32 v216, v212, v213
	v_cvt_pk_bf16_f32 v217, v214, v215
	global_store_dwordx2 v[224:225], v[216:217], off
	ds_read_b128 v[196:199], v71 offset:18432
	v_mul_f32_e32 v212, v70, v136
	v_mul_f32_e32 v213, v70, v137
	v_mul_f32_e32 v214, v70, v138
	v_mul_f32_e32 v215, v70, v139
	s_waitcnt lgkmcnt(1)
	v_mul_f32_e32 v212, v204, v212
	v_mul_f32_e32 v213, v205, v213
	v_mul_f32_e32 v214, v206, v214
	v_mul_f32_e32 v215, v207, v215
	v_cvt_pk_bf16_f32 v218, v212, v213
	v_cvt_pk_bf16_f32 v219, v214, v215
	global_store_dwordx2 v[224:225], v[218:219], off offset:512
	ds_read_b128 v[204:207], v71 offset:19456
	v_mul_f32_e32 v212, v70, v140
	v_mul_f32_e32 v213, v70, v141
	v_mul_f32_e32 v214, v70, v142
	v_mul_f32_e32 v215, v70, v143
	s_waitcnt lgkmcnt(1)
	v_mul_f32_e32 v212, v196, v212
	v_mul_f32_e32 v213, v197, v213
	v_mul_f32_e32 v214, v198, v214
	v_mul_f32_e32 v215, v199, v215
	v_cvt_pk_bf16_f32 v220, v212, v213
	v_cvt_pk_bf16_f32 v221, v214, v215
	global_store_dwordx2 v[224:225], v[220:221], off offset:1024
	ds_read_b128 v[196:199], v71 offset:20480
	v_mul_f32_e32 v212, v70, v144
	v_mul_f32_e32 v213, v70, v145
	v_mul_f32_e32 v214, v70, v146
	v_mul_f32_e32 v215, v70, v147
	s_waitcnt lgkmcnt(1)
	v_mul_f32_e32 v212, v204, v212
	v_mul_f32_e32 v213, v205, v213
	v_mul_f32_e32 v214, v206, v214
	v_mul_f32_e32 v215, v207, v215
	v_cvt_pk_bf16_f32 v222, v212, v213
	v_cvt_pk_bf16_f32 v223, v214, v215
	global_store_dwordx2 v[224:225], v[222:223], off offset:1536
	ds_read_b128 v[204:207], v71 offset:21504
	v_mul_f32_e32 v212, v70, v148
	v_mul_f32_e32 v213, v70, v149
	v_mul_f32_e32 v214, v70, v150
	v_mul_f32_e32 v215, v70, v151
	s_waitcnt lgkmcnt(1)
	v_mul_f32_e32 v212, v196, v212
	v_mul_f32_e32 v213, v197, v213
	v_mul_f32_e32 v214, v198, v214
	v_mul_f32_e32 v215, v199, v215
	v_cvt_pk_bf16_f32 v216, v212, v213
	v_cvt_pk_bf16_f32 v217, v214, v215
	global_store_dwordx2 v[224:225], v[216:217], off offset:2048
	ds_read_b128 v[196:199], v71 offset:22528
	v_mul_f32_e32 v212, v70, v152
	v_mul_f32_e32 v213, v70, v153
	v_mul_f32_e32 v214, v70, v154
	v_mul_f32_e32 v215, v70, v155
	s_waitcnt lgkmcnt(1)
	v_mul_f32_e32 v212, v204, v212
	v_mul_f32_e32 v213, v205, v213
	v_mul_f32_e32 v214, v206, v214
	v_mul_f32_e32 v215, v207, v215
	v_cvt_pk_bf16_f32 v218, v212, v213
	v_cvt_pk_bf16_f32 v219, v214, v215
	global_store_dwordx2 v[224:225], v[218:219], off offset:2560
	ds_read_b128 v[204:207], v71 offset:23552
	v_mul_f32_e32 v212, v70, v156
	v_mul_f32_e32 v213, v70, v157
	v_mul_f32_e32 v214, v70, v158
	v_mul_f32_e32 v215, v70, v159
	s_waitcnt lgkmcnt(1)
	v_mul_f32_e32 v212, v196, v212
	v_mul_f32_e32 v213, v197, v213
	v_mul_f32_e32 v214, v198, v214
	v_mul_f32_e32 v215, v199, v215
	v_cvt_pk_bf16_f32 v220, v212, v213
	v_cvt_pk_bf16_f32 v221, v214, v215
	global_store_dwordx2 v[224:225], v[220:221], off offset:3072
	ds_read_b128 v[196:199], v71 offset:24576
	v_mul_f32_e32 v212, v70, v160
	v_mul_f32_e32 v213, v70, v161
	v_mul_f32_e32 v214, v70, v162
	v_mul_f32_e32 v215, v70, v163
	s_waitcnt lgkmcnt(1)
	v_mul_f32_e32 v212, v204, v212
	v_mul_f32_e32 v213, v205, v213
	v_mul_f32_e32 v214, v206, v214
	v_mul_f32_e32 v215, v207, v215
	v_cvt_pk_bf16_f32 v222, v212, v213
	v_cvt_pk_bf16_f32 v223, v214, v215
	global_store_dwordx2 v[224:225], v[222:223], off offset:3584
	ds_read_b128 v[204:207], v71 offset:25600
	v_mul_f32_e32 v212, v70, v164
	v_mul_f32_e32 v213, v70, v165
	v_mul_f32_e32 v214, v70, v166
	v_mul_f32_e32 v215, v70, v167
	s_waitcnt lgkmcnt(1)
	v_mul_f32_e32 v212, v196, v212
	v_mul_f32_e32 v213, v197, v213
	v_mul_f32_e32 v214, v198, v214
	v_mul_f32_e32 v215, v199, v215
	v_cvt_pk_bf16_f32 v216, v212, v213
	v_cvt_pk_bf16_f32 v217, v214, v215
	global_store_dwordx2 v[226:227], v[216:217], off
	ds_read_b128 v[196:199], v71 offset:26624
	v_mul_f32_e32 v212, v70, v168
	v_mul_f32_e32 v213, v70, v169
	v_mul_f32_e32 v214, v70, v170
	v_mul_f32_e32 v215, v70, v171
	s_waitcnt lgkmcnt(1)
	v_mul_f32_e32 v212, v204, v212
	v_mul_f32_e32 v213, v205, v213
	v_mul_f32_e32 v214, v206, v214
	v_mul_f32_e32 v215, v207, v215
	v_cvt_pk_bf16_f32 v218, v212, v213
	v_cvt_pk_bf16_f32 v219, v214, v215
	global_store_dwordx2 v[226:227], v[218:219], off offset:512
	ds_read_b128 v[204:207], v71 offset:27648
	v_mul_f32_e32 v212, v70, v172
	v_mul_f32_e32 v213, v70, v173
	v_mul_f32_e32 v214, v70, v174
	v_mul_f32_e32 v215, v70, v175
	s_waitcnt lgkmcnt(1)
	v_mul_f32_e32 v212, v196, v212
	v_mul_f32_e32 v213, v197, v213
	v_mul_f32_e32 v214, v198, v214
	v_mul_f32_e32 v215, v199, v215
	v_cvt_pk_bf16_f32 v220, v212, v213
	v_cvt_pk_bf16_f32 v221, v214, v215
	global_store_dwordx2 v[226:227], v[220:221], off offset:1024
	ds_read_b128 v[196:199], v71 offset:28672
	v_mul_f32_e32 v212, v70, v176
	v_mul_f32_e32 v213, v70, v177
	v_mul_f32_e32 v214, v70, v178
	v_mul_f32_e32 v215, v70, v179
	s_waitcnt lgkmcnt(1)
	v_mul_f32_e32 v212, v204, v212
	v_mul_f32_e32 v213, v205, v213
	v_mul_f32_e32 v214, v206, v214
	v_mul_f32_e32 v215, v207, v215
	v_cvt_pk_bf16_f32 v222, v212, v213
	v_cvt_pk_bf16_f32 v223, v214, v215
	global_store_dwordx2 v[226:227], v[222:223], off offset:1536
	ds_read_b128 v[204:207], v71 offset:29696
	v_mul_f32_e32 v212, v70, v180
	v_mul_f32_e32 v213, v70, v181
	v_mul_f32_e32 v214, v70, v182
	v_mul_f32_e32 v215, v70, v183
	s_waitcnt lgkmcnt(1)
; #define LAS __attribute__((address_space(3)))
; __device__ __forceinline__ unsigned pk2(float lo, float hi) { const f32x2c v = {lo, hi}; return __builtin_bit_cast(unsigned, __builtin_convertvector(v, bf16x2c)); }
; __device__ __forceinline__ float bflo(unsigned w) { return __uint_as_float(w << 16); }
; __device__ __forceinline__ float bfhi(unsigned w) { return __uint_as_float(w & 0xffff0000u); }
; template <int MODE> ...
;     ...
;             const bf16* pr = xn + (size_t)row * DM; bf16* pw_out = xn_out + (size_t)row * DM; const bf16* hr = hb + (size_t)row * DM;
;             v2u pw[16], hw[16]; float ss = 0.f;
; #pragma unroll
;             for (int j = 0; j < 16; ++j) { pw[j] = *(const v2u*)(pr + lo4 + 256 * j); hw[j] = *(const v2u*)(hr + lo4 + 256 * j); }
;             const float ri = 1.f / rs[row];
; #pragma unroll
;             for (int j = 0; j < 16; ++j) { const float a = bflo(hw[j].x), b = bfhi(hw[j].x), c = bflo(hw[j].y), d = bfhi(hw[j].y); ss += a * a + b * b + c * c + d * d; }
;     ...
;                 for (int j = 0; j < 16; ++j) { const f32x4 g = *(const LAS f32x4*)(GP + lo4 + 256 * j), gi = *(const LAS f32x4*)(GI + lo4 + 256 * j), gn = *(const LAS f32x4*)(GN + lo4 + 256 * j);
;                     f32x4 x;
;                     x.x = bflo(pw[j].x) * ri2 * gi.x + bflo(hw[j].x) * rstdb * g.x; x.y = bfhi(pw[j].x) * ri2 * gi.y + bfhi(hw[j].x) * rstdb * g.y;
;                     x.z = bflo(pw[j].y) * ri2 * gi.z + bflo(hw[j].y) * rstdb * g.z; x.w = bfhi(pw[j].y) * ri2 * gi.w + bfhi(hw[j].y) * rstdb * g.w;
;                     v2u w; w.x = pk2(x.x * rstd2 * gn.x, x.y * rstd2 * gn.y); w.y = pk2(x.z * rstd2 * gn.z, x.w * rstd2 * gn.w);
;                     *(v2u*)(pw_out + lo4 + 256 * j) = w;
;                     if (j & 1) __builtin_amdgcn_sched_barrier(0); }
	v_mul_f32_e32 v212, v196, v212
	v_mul_f32_e32 v213, v197, v213
	v_mul_f32_e32 v214, v198, v214
	v_mul_f32_e32 v215, v199, v215
	v_cvt_pk_bf16_f32 v216, v212, v213
	v_cvt_pk_bf16_f32 v217, v214, v215
	global_store_dwordx2 v[226:227], v[216:217], off offset:2048
	ds_read_b128 v[196:199], v71 offset:30720
	v_mul_f32_e32 v212, v70, v184
	v_mul_f32_e32 v213, v70, v185
	v_mul_f32_e32 v214, v70, v186
	v_mul_f32_e32 v215, v70, v187
	s_waitcnt lgkmcnt(1)
	v_mul_f32_e32 v212, v204, v212
	v_mul_f32_e32 v213, v205, v213
	v_mul_f32_e32 v214, v206, v214
	v_mul_f32_e32 v215, v207, v215
	v_cvt_pk_bf16_f32 v218, v212, v213
	v_cvt_pk_bf16_f32 v219, v214, v215
	global_store_dwordx2 v[226:227], v[218:219], off offset:2560
	ds_read_b128 v[204:207], v71 offset:31744
	v_mul_f32_e32 v212, v70, v188
	v_mul_f32_e32 v213, v70, v189
	v_mul_f32_e32 v214, v70, v190
	v_mul_f32_e32 v215, v70, v191
	s_waitcnt lgkmcnt(1)
	v_mul_f32_e32 v212, v196, v212
	v_mul_f32_e32 v213, v197, v213
	v_mul_f32_e32 v214, v198, v214
	v_mul_f32_e32 v215, v199, v215
	v_cvt_pk_bf16_f32 v220, v212, v213
	v_cvt_pk_bf16_f32 v221, v214, v215
	global_store_dwordx2 v[226:227], v[220:221], off offset:3072
	v_mul_f32_e32 v212, v70, v192
	v_mul_f32_e32 v213, v70, v193
	v_mul_f32_e32 v214, v70, v194
	v_mul_f32_e32 v215, v70, v195
	s_waitcnt lgkmcnt(0)
	v_mul_f32_e32 v212, v204, v212
	v_mul_f32_e32 v213, v205, v213
	v_mul_f32_e32 v214, v206, v214
	v_mul_f32_e32 v215, v207, v215
	v_cvt_pk_bf16_f32 v222, v212, v213
	v_cvt_pk_bf16_f32 v223, v214, v215
	global_store_dwordx2 v[226:227], v[222:223], off offset:3584
	s_add_i32 s67, s67, s38
	s_add_u32 s64, s64, s8
	s_addc_u32 s65, s65, s9
	s_cmpk_lt_i32 s67, 0x2000
	v_lshl_add_u64 v[0:1], v[0:1], 0, s[10:11]
	s_cbranch_scc0 .LBB0_1121
.LBB0_1119:
	v_lshl_add_u64 v[68:69], v[0:1], 0, s[12:13]
	v_add_co_u32_e32 v26, vcc, 0x3000000, v68
	s_mov_b64 s[6:7], vcc
	v_add_co_u32_e32 v2, vcc, 0x7000000, v68
	s_add_u32 s62, s64, s12
	s_nop 0
	v_addc_co_u32_e32 v3, vcc, 0, v69, vcc
	global_load_dwordx2 v[60:61], v[2:3], off
	global_load_dwordx2 v[56:57], v[2:3], off offset:512
	global_load_dwordx2 v[54:55], v[2:3], off offset:1024
	global_load_dwordx2 v[50:51], v[2:3], off offset:1536
	global_load_dwordx2 v[46:47], v[2:3], off offset:2048
	global_load_dwordx2 v[44:45], v[2:3], off offset:2560
	v_add_co_u32_e32 v4, vcc, s39, v68
	s_addc_u32 s63, s65, s13
	s_nop 0
	v_addc_co_u32_e32 v5, vcc, 0, v69, vcc
	v_add_co_u32_e32 v38, vcc, s41, v68
	s_waitcnt vmcnt(5)
	v_lshlrev_b32_e32 v70, 16, v61
	v_addc_co_u32_e32 v39, vcc, 0, v69, vcc
	v_addc_co_u32_e64 v27, vcc, 0, v69, s[6:7]
	global_load_dwordx2 v[40:41], v[2:3], off offset:3072
	global_load_dwordx2 v[32:33], v[4:5], off
	global_load_dwordx2 v[28:29], v[4:5], off offset:512
	global_load_dwordx2 v[22:23], v[4:5], off offset:1024
	global_load_dwordx2 v[18:19], v[4:5], off offset:1536
	global_load_dwordx2 v[34:35], v[38:39], off
	global_load_dwordx2 v[30:31], v[38:39], off offset:512
	global_load_dwordx2 v[24:25], v[38:39], off offset:1024
	global_load_dwordx2 v[20:21], v[38:39], off offset:1536
	global_load_dwordx2 v[36:37], v[2:3], off offset:3584
	global_load_dwordx2 v[14:15], v[4:5], off offset:2048
	global_load_dwordx2 v[10:11], v[4:5], off offset:2560
	global_load_dwordx2 v[6:7], v[4:5], off offset:3072
	s_nop 0
	global_load_dwordx2 v[2:3], v[4:5], off offset:3584
	global_load_dwordx2 v[16:17], v[38:39], off offset:2048
	global_load_dwordx2 v[12:13], v[38:39], off offset:2560
	global_load_dwordx2 v[8:9], v[38:39], off offset:3072
	s_nop 0
	global_load_dwordx2 v[4:5], v[38:39], off offset:3584
	global_load_dword v78, v79, s[62:63]
	global_load_dwordx2 v[66:67], v[26:27], off
	global_load_dwordx2 v[64:65], v[26:27], off offset:512
	global_load_dwordx2 v[62:63], v[26:27], off offset:1024
	global_load_dwordx2 v[58:59], v[26:27], off offset:1536
	global_load_dwordx2 v[52:53], v[26:27], off offset:2048
	global_load_dwordx2 v[48:49], v[26:27], off offset:2560
	global_load_dwordx2 v[42:43], v[26:27], off offset:3072
	global_load_dwordx2 v[38:39], v[26:27], off offset:3584
	v_and_b32_e32 v27, 0xffff0000, v60
	s_waitcnt vmcnt(31)
	v_and_b32_e32 v74, 0xffff0000, v56
	v_lshlrev_b32_e32 v26, 16, v60
	v_lshlrev_b32_e32 v73, 16, v56
	v_mul_f32_e32 v27, v27, v27
	v_mul_f32_e32 v74, v74, v74
	v_lshlrev_b32_e32 v75, 16, v57
	s_waitcnt vmcnt(30)
	v_and_b32_e32 v80, 0xffff0000, v54
	v_fmac_f32_e32 v27, v26, v26
	v_fmac_f32_e32 v74, v73, v73
	v_and_b32_e32 v72, 0xffff0000, v61
	v_and_b32_e32 v76, 0xffff0000, v57
	v_lshlrev_b32_e32 v77, 16, v54
	s_waitcnt vmcnt(29)
	v_and_b32_e32 v84, 0xffff0000, v50
	s_waitcnt vmcnt(28)
	v_and_b32_e32 v88, 0xffff0000, v46
	v_mul_f32_e32 v80, v80, v80
	v_fmac_f32_e32 v27, v70, v70
	v_fmac_f32_e32 v74, v75, v75
	v_lshlrev_b32_e32 v81, 16, v55
	v_lshlrev_b32_e32 v83, 16, v50
	v_lshlrev_b32_e32 v87, 16, v46
	v_mul_f32_e32 v84, v84, v84
	v_fmac_f32_e32 v80, v77, v77
	v_fmac_f32_e32 v27, v72, v72
	v_fmac_f32_e32 v74, v76, v76
	v_mul_f32_e32 v72, v88, v88
	v_and_b32_e32 v82, 0xffff0000, v55
	v_lshlrev_b32_e32 v85, 16, v51
	v_fmac_f32_e32 v84, v83, v83
	v_fmac_f32_e32 v80, v81, v81
	v_add_f32_e32 v26, v27, v74
	v_lshlrev_b32_e32 v27, 16, v47
	v_fmac_f32_e32 v72, v87, v87
	v_and_b32_e32 v86, 0xffff0000, v51
	v_fmac_f32_e32 v84, v85, v85
	v_fmac_f32_e32 v80, v82, v82
	v_and_b32_e32 v70, 0xffff0000, v47
	v_fmac_f32_e32 v72, v27, v27
	v_fmac_f32_e32 v84, v86, v86
	v_add_f32_e32 v26, v26, v80
	v_fmac_f32_e32 v72, v70, v70
	s_waitcnt vmcnt(27)
; #define LAS __attribute__((address_space(3)))
; __device__ __forceinline__ float bflo(unsigned w) { return __uint_as_float(w << 16); }
; __device__ __forceinline__ float bfhi(unsigned w) { return __uint_as_float(w & 0xffff0000u); }
; #define LAUNDER_ROW(pw, hw) do { LAUNDER8(pw, 0); LAUNDER8(pw, 8); LAUNDER8(hw, 0); LAUNDER8(hw, 8); } while (0)
; template <int MODE> ...
;     ...
;             for (int j = 0; j < 16; ++j) { pw[j] = *(const v2u*)(pr + lo4 + 256 * j); hw[j] = *(const v2u*)(hr + lo4 + 256 * j); }
;             const float ri = 1.f / rs[row];
; #pragma unroll
;             for (int j = 0; j < 16; ++j) { const float a = bflo(hw[j].x), b = bfhi(hw[j].x), c = bflo(hw[j].y), d = bfhi(hw[j].y); ss += a * a + b * b + c * c + d * d; }
;             const float rstd = rsqrtf(wave_sum(ss) * (1.f / DM) + EPS);
;             asm volatile("" ::: "memory");
;             LAUNDER_ROW(pw, hw);
;             float ss2 = 0.f;
; #pragma unroll
;             for (int j = 0; j < 16; ++j) { const f32x4 g = *(const LAS f32x4*)(GP + lo4 + 256 * j), gi = *(const LAS f32x4*)(GI + lo4 + 256 * j);
;                 f32x4 x;
;                 x.x = bflo(pw[j].x) * ri * gi.x + bflo(hw[j].x) * rstd * g.x; x.y = bfhi(pw[j].x) * ri * gi.y + bfhi(hw[j].x) * rstd * g.y;
;                 x.z = bflo(pw[j].y) * ri * gi.z + bflo(hw[j].y) * rstd * g.z; x.w = bfhi(pw[j].y) * ri * gi.w + bfhi(hw[j].y) * rstd * g.w;
	v_and_b32_e32 v70, 0xffff0000, v44
	v_add_f32_e32 v26, v26, v84
	v_lshlrev_b32_e32 v27, 16, v44
	v_mul_f32_e32 v70, v70, v70
	v_add_f32_e32 v26, v26, v72
	v_lshlrev_b32_e32 v72, 16, v45
	v_fmac_f32_e32 v70, v27, v27
	v_and_b32_e32 v73, 0xffff0000, v45
	v_fmac_f32_e32 v70, v72, v72
	v_fmac_f32_e32 v70, v73, v73
	v_add_f32_e32 v26, v26, v70
	s_waitcnt vmcnt(26)
	v_and_b32_e32 v70, 0xffff0000, v40
	v_lshlrev_b32_e32 v27, 16, v40
	v_mul_f32_e32 v70, v70, v70
	v_lshlrev_b32_e32 v72, 16, v41
	v_fmac_f32_e32 v70, v27, v27
	v_and_b32_e32 v73, 0xffff0000, v41
	v_fmac_f32_e32 v70, v72, v72
	v_fmac_f32_e32 v70, v73, v73
	v_add_f32_e32 v26, v26, v70
	s_waitcnt vmcnt(17)
	v_and_b32_e32 v70, 0xffff0000, v36
	v_lshlrev_b32_e32 v27, 16, v36
	v_mul_f32_e32 v70, v70, v70
	v_lshlrev_b32_e32 v72, 16, v37
	v_fmac_f32_e32 v70, v27, v27
	v_and_b32_e32 v73, 0xffff0000, v37
	v_fmac_f32_e32 v70, v72, v72
	v_fmac_f32_e32 v70, v73, v73
	v_add_f32_e32 v26, v26, v70
	v_and_b32_e32 v70, 0xffff0000, v34
	v_lshlrev_b32_e32 v27, 16, v34
	v_mul_f32_e32 v70, v70, v70
	v_lshlrev_b32_e32 v72, 16, v35
	v_fmac_f32_e32 v70, v27, v27
	v_and_b32_e32 v73, 0xffff0000, v35
	v_fmac_f32_e32 v70, v72, v72
	v_fmac_f32_e32 v70, v73, v73
	v_add_f32_e32 v26, v26, v70
	v_and_b32_e32 v70, 0xffff0000, v30
	v_lshlrev_b32_e32 v27, 16, v30
	v_mul_f32_e32 v70, v70, v70
	v_lshlrev_b32_e32 v72, 16, v31
	v_fmac_f32_e32 v70, v27, v27
	v_and_b32_e32 v73, 0xffff0000, v31
	v_fmac_f32_e32 v70, v72, v72
	v_fmac_f32_e32 v70, v73, v73
	v_add_f32_e32 v26, v26, v70
	v_and_b32_e32 v70, 0xffff0000, v24
	v_lshlrev_b32_e32 v27, 16, v24
	v_mul_f32_e32 v70, v70, v70
	v_lshlrev_b32_e32 v72, 16, v25
	v_fmac_f32_e32 v70, v27, v27
	v_and_b32_e32 v73, 0xffff0000, v25
	v_fmac_f32_e32 v70, v72, v72
	v_fmac_f32_e32 v70, v73, v73
	v_add_f32_e32 v26, v26, v70
	v_and_b32_e32 v70, 0xffff0000, v20
	v_lshlrev_b32_e32 v27, 16, v20
	v_mul_f32_e32 v70, v70, v70
	v_lshlrev_b32_e32 v72, 16, v21
	v_fmac_f32_e32 v70, v27, v27
	v_and_b32_e32 v73, 0xffff0000, v21
	v_fmac_f32_e32 v70, v72, v72
	v_fmac_f32_e32 v70, v73, v73
	s_waitcnt vmcnt(11)
	v_and_b32_e32 v73, 0xffff0000, v12
	v_and_b32_e32 v72, 0xffff0000, v16
	v_add_f32_e32 v70, v26, v70
	v_lshlrev_b32_e32 v27, 16, v12
	v_lshlrev_b32_e32 v26, 16, v16
	v_pk_mul_f32 v[72:73], v[72:73], v[72:73]
	v_lshlrev_b32_e32 v75, 16, v13
	v_lshlrev_b32_e32 v74, 16, v17
	v_pk_fma_f32 v[26:27], v[26:27], v[26:27], v[72:73]
	v_and_b32_e32 v77, 0xffff0000, v13
	v_and_b32_e32 v76, 0xffff0000, v17
	v_pk_fma_f32 v[26:27], v[74:75], v[74:75], v[26:27]
	s_waitcnt vmcnt(9)
	v_and_b32_e32 v73, 0xffff0000, v4
	v_pk_fma_f32 v[26:27], v[76:77], v[76:77], v[26:27]
	v_and_b32_e32 v72, 0xffff0000, v8
	v_add_f32_e32 v26, v70, v26
	v_add_f32_e32 v70, v26, v27
	v_lshlrev_b32_e32 v27, 16, v4
	v_lshlrev_b32_e32 v26, 16, v8
	v_pk_mul_f32 v[72:73], v[72:73], v[72:73]
	v_lshlrev_b32_e32 v75, 16, v5
	v_lshlrev_b32_e32 v74, 16, v9
	v_pk_fma_f32 v[26:27], v[26:27], v[26:27], v[72:73]
	v_and_b32_e32 v77, 0xffff0000, v5
	v_and_b32_e32 v76, 0xffff0000, v9
	v_pk_fma_f32 v[26:27], v[74:75], v[74:75], v[26:27]
	s_waitcnt vmcnt(0)
	v_pk_fma_f32 v[26:27], v[76:77], v[76:77], v[26:27]
	v_div_scale_f32 v77, s[6:7], v78, v78, 1.0
	v_add_f32_e32 v26, v70, v26
	v_add_f32_e32 v26, v26, v27
	v_and_b32_e32 v27, 64, v101
	v_add_u32_e32 v27, 64, v27
	v_xor_b32_e32 v70, 1, v101
	v_cmp_lt_i32_e32 vcc, v70, v27
	v_rcp_f32_e32 v80, v77
	s_nop 0
	v_cndmask_b32_e32 v70, v101, v70, vcc
	v_lshlrev_b32_e32 v70, 2, v70
	ds_bpermute_b32 v72, v70, v26
	v_fma_f32 v81, -v77, v80, 1.0
	v_fmac_f32_e32 v80, v81, v80
	s_waitcnt lgkmcnt(0)
	v_add_f32_e32 v26, v26, v72
	v_xor_b32_e32 v72, 2, v101
	v_cmp_lt_i32_e32 vcc, v72, v27
	s_nop 1
	v_cndmask_b32_e32 v72, v101, v72, vcc
	v_lshlrev_b32_e32 v72, 2, v72
	ds_bpermute_b32 v73, v72, v26
	s_waitcnt lgkmcnt(0)
	v_add_f32_e32 v26, v26, v73
	v_xor_b32_e32 v73, 4, v101
	v_cmp_lt_i32_e32 vcc, v73, v27
	s_nop 1
	v_cndmask_b32_e32 v73, v101, v73, vcc
	v_lshlrev_b32_e32 v73, 2, v73
	ds_bpermute_b32 v74, v73, v26
	s_waitcnt lgkmcnt(0)
	v_add_f32_e32 v26, v26, v74
	v_xor_b32_e32 v74, 8, v101
	v_cmp_lt_i32_e32 vcc, v74, v27
	s_nop 1
	v_cndmask_b32_e32 v74, v101, v74, vcc
	v_lshlrev_b32_e32 v74, 2, v74
	ds_bpermute_b32 v75, v74, v26
	s_waitcnt lgkmcnt(0)
	v_add_f32_e32 v26, v26, v75
	v_xor_b32_e32 v75, 16, v101
	v_cmp_lt_i32_e32 vcc, v75, v27
	s_nop 1
	v_cndmask_b32_e32 v75, v101, v75, vcc
	v_lshlrev_b32_e32 v75, 2, v75
	ds_bpermute_b32 v76, v75, v26
	v_div_scale_f32 v81, vcc, 1.0, v78, 1.0
	v_mul_f32_e32 v82, v81, v80
	v_fma_f32 v83, -v77, v82, v81
	s_waitcnt lgkmcnt(0)
	v_add_f32_e32 v26, v26, v76
	v_xor_b32_e32 v76, 32, v101
	v_cmp_lt_i32_e64 s[6:7], v76, v27
	v_fmac_f32_e32 v82, v83, v80
	v_fma_f32 v77, -v77, v82, v81
	v_cndmask_b32_e64 v27, v101, v76, s[6:7]
	v_lshlrev_b32_e32 v76, 2, v27
	ds_bpermute_b32 v27, v76, v26
	s_waitcnt lgkmcnt(0)
	v_add_f32_e32 v26, v26, v27
	v_fmamk_f32 v26, v26, 0x39800000, v100
	v_mul_f32_e32 v27, 0x4b800000, v26
	v_cmp_gt_f32_e64 s[6:7], s66, v26
	s_nop 1
	v_cndmask_b32_e64 v26, v26, v27, s[6:7]
	v_rsq_f32_e32 v27, v26
	v_div_fmas_f32 v26, v77, v80, v82
	v_div_fixup_f32 v26, v26, v78, 1.0
	v_mul_f32_e32 v77, 0x45800000, v27
	v_cndmask_b32_e64 v27, v27, v77, s[6:7]
	ds_read_b128 v[196:199], v71
	ds_read_b128 v[200:203], v71 offset:32768
	ds_read_b128 v[204:207], v71 offset:1024
	ds_read_b128 v[208:211], v71 offset:33792
	v_lshlrev_b32_e32 v212, 16, v66
	v_and_b32_e32 v213, 0xffff0000, v66
	v_lshlrev_b32_e32 v214, 16, v67
	v_and_b32_e32 v215, 0xffff0000, v67
	v_lshlrev_b32_e32 v216, 16, v60
	v_and_b32_e32 v217, 0xffff0000, v60
	v_lshlrev_b32_e32 v218, 16, v61
	v_and_b32_e32 v219, 0xffff0000, v61
	v_mul_f32_e32 v212, v26, v212
	v_mul_f32_e32 v213, v26, v213
	v_mul_f32_e32 v214, v26, v214
	v_mul_f32_e32 v215, v26, v215
	v_mul_f32_e32 v216, v27, v216
	v_mul_f32_e32 v217, v27, v217
	v_mul_f32_e32 v218, v27, v218
	v_mul_f32_e32 v219, v27, v219
	s_waitcnt lgkmcnt(2)
; #define LAS __attribute__((address_space(3)))
; __device__ __forceinline__ float bflo(unsigned w) { return __uint_as_float(w << 16); }
; __device__ __forceinline__ float bfhi(unsigned w) { return __uint_as_float(w & 0xffff0000u); }
; template <int MODE> ...
;     ...
;             for (int j = 0; j < 16; ++j) { const f32x4 g = *(const LAS f32x4*)(GP + lo4 + 256 * j), gi = *(const LAS f32x4*)(GI + lo4 + 256 * j);
;                 f32x4 x;
;                 x.x = bflo(pw[j].x) * ri * gi.x + bflo(hw[j].x) * rstd * g.x; x.y = bfhi(pw[j].x) * ri * gi.y + bfhi(hw[j].x) * rstd * g.y;
;                 x.z = bflo(pw[j].y) * ri * gi.z + bflo(hw[j].y) * rstd * g.z; x.w = bfhi(pw[j].y) * ri * gi.w + bfhi(hw[j].y) * rstd * g.w;
;                 if (MODE == 2) *(f32x4*)(xout + (size_t)row * DM + lo4 + 256 * j) = x;
;                 else ss2 += x.x * x.x + x.y * x.y + x.z * x.z + x.w * x.w;
;                 if (j & 1) __builtin_amdgcn_sched_barrier(0); }
	v_mul_f32_e32 v132, v212, v200
	v_mul_f32_e32 v133, v213, v201
	v_mul_f32_e32 v134, v214, v202
	v_mul_f32_e32 v135, v215, v203
	v_fmac_f32_e32 v132, v196, v216
	v_fmac_f32_e32 v133, v197, v217
	v_fmac_f32_e32 v134, v198, v218
	v_fmac_f32_e32 v135, v199, v219
	v_mul_f32_e32 v77, v133, v133
	v_fmac_f32_e32 v77, v132, v132
	v_fmac_f32_e32 v77, v134, v134
	v_fmac_f32_e32 v77, v135, v135
	ds_read_b128 v[196:199], v71 offset:2048
	ds_read_b128 v[200:203], v71 offset:34816
	v_lshlrev_b32_e32 v212, 16, v64
	v_and_b32_e32 v213, 0xffff0000, v64
	v_lshlrev_b32_e32 v214, 16, v65
	v_and_b32_e32 v215, 0xffff0000, v65
	v_lshlrev_b32_e32 v216, 16, v56
	v_and_b32_e32 v217, 0xffff0000, v56
	v_lshlrev_b32_e32 v218, 16, v57
	v_and_b32_e32 v219, 0xffff0000, v57
	v_mul_f32_e32 v212, v26, v212
	v_mul_f32_e32 v213, v26, v213
	v_mul_f32_e32 v214, v26, v214
	v_mul_f32_e32 v215, v26, v215
	v_mul_f32_e32 v216, v27, v216
	v_mul_f32_e32 v217, v27, v217
	v_mul_f32_e32 v218, v27, v218
	v_mul_f32_e32 v219, v27, v219
	s_waitcnt lgkmcnt(2)
	v_mul_f32_e32 v136, v212, v208
	v_mul_f32_e32 v137, v213, v209
	v_mul_f32_e32 v138, v214, v210
	v_mul_f32_e32 v139, v215, v211
	v_fmac_f32_e32 v136, v204, v216
	v_fmac_f32_e32 v137, v205, v217
	v_fmac_f32_e32 v138, v206, v218
	v_fmac_f32_e32 v139, v207, v219
	v_mul_f32_e32 v212, v137, v137
	v_fmac_f32_e32 v212, v136, v136
	v_fmac_f32_e32 v212, v138, v138
	v_fmac_f32_e32 v212, v139, v139
	v_add_f32_e32 v77, v77, v212
	ds_read_b128 v[204:207], v71 offset:3072
	ds_read_b128 v[208:211], v71 offset:35840
	v_lshlrev_b32_e32 v212, 16, v62
	v_and_b32_e32 v213, 0xffff0000, v62
	v_lshlrev_b32_e32 v214, 16, v63
	v_and_b32_e32 v215, 0xffff0000, v63
	v_lshlrev_b32_e32 v216, 16, v54
	v_and_b32_e32 v217, 0xffff0000, v54
	v_lshlrev_b32_e32 v218, 16, v55
	v_and_b32_e32 v219, 0xffff0000, v55
	v_mul_f32_e32 v212, v26, v212
	v_mul_f32_e32 v213, v26, v213
	v_mul_f32_e32 v214, v26, v214
	v_mul_f32_e32 v215, v26, v215
	v_mul_f32_e32 v216, v27, v216
	v_mul_f32_e32 v217, v27, v217
	v_mul_f32_e32 v218, v27, v218
	v_mul_f32_e32 v219, v27, v219
	s_waitcnt lgkmcnt(2)
	v_mul_f32_e32 v140, v212, v200
	v_mul_f32_e32 v141, v213, v201
	v_mul_f32_e32 v142, v214, v202
	v_mul_f32_e32 v143, v215, v203
	v_fmac_f32_e32 v140, v196, v216
	v_fmac_f32_e32 v141, v197, v217
	v_fmac_f32_e32 v142, v198, v218
	v_fmac_f32_e32 v143, v199, v219
	v_mul_f32_e32 v212, v141, v141
	v_fmac_f32_e32 v212, v140, v140
	v_fmac_f32_e32 v212, v142, v142
	v_fmac_f32_e32 v212, v143, v143
	v_add_f32_e32 v77, v77, v212
	ds_read_b128 v[196:199], v71 offset:4096
	ds_read_b128 v[200:203], v71 offset:36864
	v_lshlrev_b32_e32 v212, 16, v58
	v_and_b32_e32 v213, 0xffff0000, v58
	v_lshlrev_b32_e32 v214, 16, v59
	v_and_b32_e32 v215, 0xffff0000, v59
	v_lshlrev_b32_e32 v216, 16, v50
	v_and_b32_e32 v217, 0xffff0000, v50
	v_lshlrev_b32_e32 v218, 16, v51
	v_and_b32_e32 v219, 0xffff0000, v51
	v_mul_f32_e32 v212, v26, v212
	v_mul_f32_e32 v213, v26, v213
	v_mul_f32_e32 v214, v26, v214
	v_mul_f32_e32 v215, v26, v215
	v_mul_f32_e32 v216, v27, v216
	v_mul_f32_e32 v217, v27, v217
	v_mul_f32_e32 v218, v27, v218
	v_mul_f32_e32 v219, v27, v219
	s_waitcnt lgkmcnt(2)
	v_mul_f32_e32 v144, v212, v208
	v_mul_f32_e32 v145, v213, v209
	v_mul_f32_e32 v146, v214, v210
	v_mul_f32_e32 v147, v215, v211
	v_fmac_f32_e32 v144, v204, v216
	v_fmac_f32_e32 v145, v205, v217
	v_fmac_f32_e32 v146, v206, v218
	v_fmac_f32_e32 v147, v207, v219
	v_mul_f32_e32 v212, v145, v145
	v_fmac_f32_e32 v212, v144, v144
	v_fmac_f32_e32 v212, v146, v146
	v_fmac_f32_e32 v212, v147, v147
	v_add_f32_e32 v77, v77, v212
	ds_read_b128 v[204:207], v71 offset:5120
	ds_read_b128 v[208:211], v71 offset:37888
	v_lshlrev_b32_e32 v212, 16, v52
	v_and_b32_e32 v213, 0xffff0000, v52
	v_lshlrev_b32_e32 v214, 16, v53
	v_and_b32_e32 v215, 0xffff0000, v53
	v_lshlrev_b32_e32 v216, 16, v46
	v_and_b32_e32 v217, 0xffff0000, v46
	v_lshlrev_b32_e32 v218, 16, v47
	v_and_b32_e32 v219, 0xffff0000, v47
	v_mul_f32_e32 v212, v26, v212
	v_mul_f32_e32 v213, v26, v213
	v_mul_f32_e32 v214, v26, v214
	v_mul_f32_e32 v215, v26, v215
	v_mul_f32_e32 v216, v27, v216
	v_mul_f32_e32 v217, v27, v217
	v_mul_f32_e32 v218, v27, v218
	v_mul_f32_e32 v219, v27, v219
	s_waitcnt lgkmcnt(2)
	v_mul_f32_e32 v148, v212, v200
	v_mul_f32_e32 v149, v213, v201
	v_mul_f32_e32 v150, v214, v202
	v_mul_f32_e32 v151, v215, v203
	v_fmac_f32_e32 v148, v196, v216
	v_fmac_f32_e32 v149, v197, v217
	v_fmac_f32_e32 v150, v198, v218
	v_fmac_f32_e32 v151, v199, v219
	v_mul_f32_e32 v212, v149, v149
	v_fmac_f32_e32 v212, v148, v148
	v_fmac_f32_e32 v212, v150, v150
	v_fmac_f32_e32 v212, v151, v151
	v_add_f32_e32 v77, v77, v212
	ds_read_b128 v[196:199], v71 offset:6144
	ds_read_b128 v[200:203], v71 offset:38912
	v_lshlrev_b32_e32 v212, 16, v48
	v_and_b32_e32 v213, 0xffff0000, v48
	v_lshlrev_b32_e32 v214, 16, v49
	v_and_b32_e32 v215, 0xffff0000, v49
	v_lshlrev_b32_e32 v216, 16, v44
	v_and_b32_e32 v217, 0xffff0000, v44
	v_lshlrev_b32_e32 v218, 16, v45
	v_and_b32_e32 v219, 0xffff0000, v45
	v_mul_f32_e32 v212, v26, v212
	v_mul_f32_e32 v213, v26, v213
	v_mul_f32_e32 v214, v26, v214
	v_mul_f32_e32 v215, v26, v215
	v_mul_f32_e32 v216, v27, v216
	v_mul_f32_e32 v217, v27, v217
	v_mul_f32_e32 v218, v27, v218
	v_mul_f32_e32 v219, v27, v219
	s_waitcnt lgkmcnt(2)
; #define LAS __attribute__((address_space(3)))
; __device__ __forceinline__ float bflo(unsigned w) { return __uint_as_float(w << 16); }
; __device__ __forceinline__ float bfhi(unsigned w) { return __uint_as_float(w & 0xffff0000u); }
; template <int MODE> ...
;     ...
;             for (int j = 0; j < 16; ++j) { const f32x4 g = *(const LAS f32x4*)(GP + lo4 + 256 * j), gi = *(const LAS f32x4*)(GI + lo4 + 256 * j);
;                 f32x4 x;
;                 x.x = bflo(pw[j].x) * ri * gi.x + bflo(hw[j].x) * rstd * g.x; x.y = bfhi(pw[j].x) * ri * gi.y + bfhi(hw[j].x) * rstd * g.y;
;                 x.z = bflo(pw[j].y) * ri * gi.z + bflo(hw[j].y) * rstd * g.z; x.w = bfhi(pw[j].y) * ri * gi.w + bfhi(hw[j].y) * rstd * g.w;
;                 if (MODE == 2) *(f32x4*)(xout + (size_t)row * DM + lo4 + 256 * j) = x;
;                 else ss2 += x.x * x.x + x.y * x.y + x.z * x.z + x.w * x.w;
;                 if (j & 1) __builtin_amdgcn_sched_barrier(0); }
	v_mul_f32_e32 v152, v212, v208
	v_mul_f32_e32 v153, v213, v209
	v_mul_f32_e32 v154, v214, v210
	v_mul_f32_e32 v155, v215, v211
	v_fmac_f32_e32 v152, v204, v216
	v_fmac_f32_e32 v153, v205, v217
	v_fmac_f32_e32 v154, v206, v218
	v_fmac_f32_e32 v155, v207, v219
	v_mul_f32_e32 v212, v153, v153
	v_fmac_f32_e32 v212, v152, v152
	v_fmac_f32_e32 v212, v154, v154
	v_fmac_f32_e32 v212, v155, v155
	v_add_f32_e32 v77, v77, v212
	ds_read_b128 v[204:207], v71 offset:7168
	ds_read_b128 v[208:211], v71 offset:39936
	v_lshlrev_b32_e32 v212, 16, v42
	v_and_b32_e32 v213, 0xffff0000, v42
	v_lshlrev_b32_e32 v214, 16, v43
	v_and_b32_e32 v215, 0xffff0000, v43
	v_lshlrev_b32_e32 v216, 16, v40
	v_and_b32_e32 v217, 0xffff0000, v40
	v_lshlrev_b32_e32 v218, 16, v41
	v_and_b32_e32 v219, 0xffff0000, v41
	v_mul_f32_e32 v212, v26, v212
	v_mul_f32_e32 v213, v26, v213
	v_mul_f32_e32 v214, v26, v214
	v_mul_f32_e32 v215, v26, v215
	v_mul_f32_e32 v216, v27, v216
	v_mul_f32_e32 v217, v27, v217
	v_mul_f32_e32 v218, v27, v218
	v_mul_f32_e32 v219, v27, v219
	s_waitcnt lgkmcnt(2)
	v_mul_f32_e32 v156, v212, v200
	v_mul_f32_e32 v157, v213, v201
	v_mul_f32_e32 v158, v214, v202
	v_mul_f32_e32 v159, v215, v203
	v_fmac_f32_e32 v156, v196, v216
	v_fmac_f32_e32 v157, v197, v217
	v_fmac_f32_e32 v158, v198, v218
	v_fmac_f32_e32 v159, v199, v219
	v_mul_f32_e32 v212, v157, v157
	v_fmac_f32_e32 v212, v156, v156
	v_fmac_f32_e32 v212, v158, v158
	v_fmac_f32_e32 v212, v159, v159
	v_add_f32_e32 v77, v77, v212
	ds_read_b128 v[196:199], v71 offset:8192
	ds_read_b128 v[200:203], v71 offset:40960
	v_lshlrev_b32_e32 v212, 16, v38
	v_and_b32_e32 v213, 0xffff0000, v38
	v_lshlrev_b32_e32 v214, 16, v39
	v_and_b32_e32 v215, 0xffff0000, v39
	v_lshlrev_b32_e32 v216, 16, v36
	v_and_b32_e32 v217, 0xffff0000, v36
	v_lshlrev_b32_e32 v218, 16, v37
	v_and_b32_e32 v219, 0xffff0000, v37
	v_mul_f32_e32 v212, v26, v212
	v_mul_f32_e32 v213, v26, v213
	v_mul_f32_e32 v214, v26, v214
	v_mul_f32_e32 v215, v26, v215
	v_mul_f32_e32 v216, v27, v216
	v_mul_f32_e32 v217, v27, v217
	v_mul_f32_e32 v218, v27, v218
	v_mul_f32_e32 v219, v27, v219
	s_waitcnt lgkmcnt(2)
	v_mul_f32_e32 v160, v212, v208
	v_mul_f32_e32 v161, v213, v209
	v_mul_f32_e32 v162, v214, v210
	v_mul_f32_e32 v163, v215, v211
	v_fmac_f32_e32 v160, v204, v216
	v_fmac_f32_e32 v161, v205, v217
	v_fmac_f32_e32 v162, v206, v218
	v_fmac_f32_e32 v163, v207, v219
	v_mul_f32_e32 v212, v161, v161
	v_fmac_f32_e32 v212, v160, v160
	v_fmac_f32_e32 v212, v162, v162
	v_fmac_f32_e32 v212, v163, v163
	v_add_f32_e32 v77, v77, v212
	ds_read_b128 v[204:207], v71 offset:9216
	ds_read_b128 v[208:211], v71 offset:41984
	v_lshlrev_b32_e32 v212, 16, v32
	v_and_b32_e32 v213, 0xffff0000, v32
	v_lshlrev_b32_e32 v214, 16, v33
	v_and_b32_e32 v215, 0xffff0000, v33
	v_lshlrev_b32_e32 v216, 16, v34
	v_and_b32_e32 v217, 0xffff0000, v34
	v_lshlrev_b32_e32 v218, 16, v35
	v_and_b32_e32 v219, 0xffff0000, v35
	v_mul_f32_e32 v212, v26, v212
	v_mul_f32_e32 v213, v26, v213
	v_mul_f32_e32 v214, v26, v214
	v_mul_f32_e32 v215, v26, v215
	v_mul_f32_e32 v216, v27, v216
	v_mul_f32_e32 v217, v27, v217
	v_mul_f32_e32 v218, v27, v218
	v_mul_f32_e32 v219, v27, v219
	s_waitcnt lgkmcnt(2)
	v_mul_f32_e32 v164, v212, v200
	v_mul_f32_e32 v165, v213, v201
	v_mul_f32_e32 v166, v214, v202
	v_mul_f32_e32 v167, v215, v203
	v_fmac_f32_e32 v164, v196, v216
	v_fmac_f32_e32 v165, v197, v217
	v_fmac_f32_e32 v166, v198, v218
	v_fmac_f32_e32 v167, v199, v219
	v_mul_f32_e32 v212, v165, v165
	v_fmac_f32_e32 v212, v164, v164
	v_fmac_f32_e32 v212, v166, v166
	v_fmac_f32_e32 v212, v167, v167
	v_add_f32_e32 v77, v77, v212
	ds_read_b128 v[196:199], v71 offset:10240
	ds_read_b128 v[200:203], v71 offset:43008
	v_lshlrev_b32_e32 v212, 16, v28
	v_and_b32_e32 v213, 0xffff0000, v28
	v_lshlrev_b32_e32 v214, 16, v29
	v_and_b32_e32 v215, 0xffff0000, v29
	v_lshlrev_b32_e32 v216, 16, v30
	v_and_b32_e32 v217, 0xffff0000, v30
	v_lshlrev_b32_e32 v218, 16, v31
	v_and_b32_e32 v219, 0xffff0000, v31
	v_mul_f32_e32 v212, v26, v212
	v_mul_f32_e32 v213, v26, v213
	v_mul_f32_e32 v214, v26, v214
	v_mul_f32_e32 v215, v26, v215
	v_mul_f32_e32 v216, v27, v216
	v_mul_f32_e32 v217, v27, v217
	v_mul_f32_e32 v218, v27, v218
	v_mul_f32_e32 v219, v27, v219
	s_waitcnt lgkmcnt(2)
	v_mul_f32_e32 v168, v212, v208
	v_mul_f32_e32 v169, v213, v209
	v_mul_f32_e32 v170, v214, v210
	v_mul_f32_e32 v171, v215, v211
	v_fmac_f32_e32 v168, v204, v216
	v_fmac_f32_e32 v169, v205, v217
	v_fmac_f32_e32 v170, v206, v218
	v_fmac_f32_e32 v171, v207, v219
	v_mul_f32_e32 v212, v169, v169
	v_fmac_f32_e32 v212, v168, v168
	v_fmac_f32_e32 v212, v170, v170
	v_fmac_f32_e32 v212, v171, v171
	v_add_f32_e32 v77, v77, v212
	ds_read_b128 v[204:207], v71 offset:11264
	ds_read_b128 v[208:211], v71 offset:44032
	v_lshlrev_b32_e32 v212, 16, v22
	v_and_b32_e32 v213, 0xffff0000, v22
	v_lshlrev_b32_e32 v214, 16, v23
	v_and_b32_e32 v215, 0xffff0000, v23
	v_lshlrev_b32_e32 v216, 16, v24
	v_and_b32_e32 v217, 0xffff0000, v24
	v_lshlrev_b32_e32 v218, 16, v25
	v_and_b32_e32 v219, 0xffff0000, v25
	v_mul_f32_e32 v212, v26, v212
	v_mul_f32_e32 v213, v26, v213
	v_mul_f32_e32 v214, v26, v214
	v_mul_f32_e32 v215, v26, v215
	v_mul_f32_e32 v216, v27, v216
	v_mul_f32_e32 v217, v27, v217
	v_mul_f32_e32 v218, v27, v218
	v_mul_f32_e32 v219, v27, v219
	s_waitcnt lgkmcnt(2)
; #define LAS __attribute__((address_space(3)))
; __device__ __forceinline__ float bflo(unsigned w) { return __uint_as_float(w << 16); }
; __device__ __forceinline__ float bfhi(unsigned w) { return __uint_as_float(w & 0xffff0000u); }
; template <int MODE> ...
;     ...
;             for (int j = 0; j < 16; ++j) { const f32x4 g = *(const LAS f32x4*)(GP + lo4 + 256 * j), gi = *(const LAS f32x4*)(GI + lo4 + 256 * j);
;                 f32x4 x;
;                 x.x = bflo(pw[j].x) * ri * gi.x + bflo(hw[j].x) * rstd * g.x; x.y = bfhi(pw[j].x) * ri * gi.y + bfhi(hw[j].x) * rstd * g.y;
;                 x.z = bflo(pw[j].y) * ri * gi.z + bflo(hw[j].y) * rstd * g.z; x.w = bfhi(pw[j].y) * ri * gi.w + bfhi(hw[j].y) * rstd * g.w;
;                 if (MODE == 2) *(f32x4*)(xout + (size_t)row * DM + lo4 + 256 * j) = x;
;                 else ss2 += x.x * x.x + x.y * x.y + x.z * x.z + x.w * x.w;
;                 if (j & 1) __builtin_amdgcn_sched_barrier(0); }
;             if (MODE == 1) {
;                 const float rstd2 = rsqrtf(wave_sum(ss2) * (1.f / DM) + EPS);
;                 if (lane == 0) rs_out[row] = rstd2;
	v_mul_f32_e32 v172, v212, v200
	v_mul_f32_e32 v173, v213, v201
	v_mul_f32_e32 v174, v214, v202
	v_mul_f32_e32 v175, v215, v203
	v_fmac_f32_e32 v172, v196, v216
	v_fmac_f32_e32 v173, v197, v217
	v_fmac_f32_e32 v174, v198, v218
	v_fmac_f32_e32 v175, v199, v219
	v_mul_f32_e32 v212, v173, v173
	v_fmac_f32_e32 v212, v172, v172
	v_fmac_f32_e32 v212, v174, v174
	v_fmac_f32_e32 v212, v175, v175
	v_add_f32_e32 v77, v77, v212
	ds_read_b128 v[196:199], v71 offset:12288
	ds_read_b128 v[200:203], v71 offset:45056
	v_lshlrev_b32_e32 v212, 16, v18
	v_and_b32_e32 v213, 0xffff0000, v18
	v_lshlrev_b32_e32 v214, 16, v19
	v_and_b32_e32 v215, 0xffff0000, v19
	v_lshlrev_b32_e32 v216, 16, v20
	v_and_b32_e32 v217, 0xffff0000, v20
	v_lshlrev_b32_e32 v218, 16, v21
	v_and_b32_e32 v219, 0xffff0000, v21
	v_mul_f32_e32 v212, v26, v212
	v_mul_f32_e32 v213, v26, v213
	v_mul_f32_e32 v214, v26, v214
	v_mul_f32_e32 v215, v26, v215
	v_mul_f32_e32 v216, v27, v216
	v_mul_f32_e32 v217, v27, v217
	v_mul_f32_e32 v218, v27, v218
	v_mul_f32_e32 v219, v27, v219
	s_waitcnt lgkmcnt(2)
	v_mul_f32_e32 v176, v212, v208
	v_mul_f32_e32 v177, v213, v209
	v_mul_f32_e32 v178, v214, v210
	v_mul_f32_e32 v179, v215, v211
	v_fmac_f32_e32 v176, v204, v216
	v_fmac_f32_e32 v177, v205, v217
	v_fmac_f32_e32 v178, v206, v218
	v_fmac_f32_e32 v179, v207, v219
	v_mul_f32_e32 v212, v177, v177
	v_fmac_f32_e32 v212, v176, v176
	v_fmac_f32_e32 v212, v178, v178
	v_fmac_f32_e32 v212, v179, v179
	v_add_f32_e32 v77, v77, v212
	ds_read_b128 v[204:207], v71 offset:13312
	ds_read_b128 v[208:211], v71 offset:46080
	v_lshlrev_b32_e32 v212, 16, v14
	v_and_b32_e32 v213, 0xffff0000, v14
	v_lshlrev_b32_e32 v214, 16, v15
	v_and_b32_e32 v215, 0xffff0000, v15
	v_lshlrev_b32_e32 v216, 16, v16
	v_and_b32_e32 v217, 0xffff0000, v16
	v_lshlrev_b32_e32 v218, 16, v17
	v_and_b32_e32 v219, 0xffff0000, v17
	v_mul_f32_e32 v212, v26, v212
	v_mul_f32_e32 v213, v26, v213
	v_mul_f32_e32 v214, v26, v214
	v_mul_f32_e32 v215, v26, v215
	v_mul_f32_e32 v216, v27, v216
	v_mul_f32_e32 v217, v27, v217
	v_mul_f32_e32 v218, v27, v218
	v_mul_f32_e32 v219, v27, v219
	s_waitcnt lgkmcnt(2)
	v_mul_f32_e32 v180, v212, v200
	v_mul_f32_e32 v181, v213, v201
	v_mul_f32_e32 v182, v214, v202
	v_mul_f32_e32 v183, v215, v203
	v_fmac_f32_e32 v180, v196, v216
	v_fmac_f32_e32 v181, v197, v217
	v_fmac_f32_e32 v182, v198, v218
	v_fmac_f32_e32 v183, v199, v219
	v_mul_f32_e32 v212, v181, v181
	v_fmac_f32_e32 v212, v180, v180
	v_fmac_f32_e32 v212, v182, v182
	v_fmac_f32_e32 v212, v183, v183
	v_add_f32_e32 v77, v77, v212
	ds_read_b128 v[196:199], v71 offset:14336
	ds_read_b128 v[200:203], v71 offset:47104
	v_lshlrev_b32_e32 v212, 16, v10
	v_and_b32_e32 v213, 0xffff0000, v10
	v_lshlrev_b32_e32 v214, 16, v11
	v_and_b32_e32 v215, 0xffff0000, v11
	v_lshlrev_b32_e32 v216, 16, v12
	v_and_b32_e32 v217, 0xffff0000, v12
	v_lshlrev_b32_e32 v218, 16, v13
	v_and_b32_e32 v219, 0xffff0000, v13
	v_mul_f32_e32 v212, v26, v212
	v_mul_f32_e32 v213, v26, v213
	v_mul_f32_e32 v214, v26, v214
	v_mul_f32_e32 v215, v26, v215
	v_mul_f32_e32 v216, v27, v216
	v_mul_f32_e32 v217, v27, v217
	v_mul_f32_e32 v218, v27, v218
	v_mul_f32_e32 v219, v27, v219
	s_waitcnt lgkmcnt(2)
	v_mul_f32_e32 v184, v212, v208
	v_mul_f32_e32 v185, v213, v209
	v_mul_f32_e32 v186, v214, v210
	v_mul_f32_e32 v187, v215, v211
	v_fmac_f32_e32 v184, v204, v216
	v_fmac_f32_e32 v185, v205, v217
	v_fmac_f32_e32 v186, v206, v218
	v_fmac_f32_e32 v187, v207, v219
	v_mul_f32_e32 v212, v185, v185
	v_fmac_f32_e32 v212, v184, v184
	v_fmac_f32_e32 v212, v186, v186
	v_fmac_f32_e32 v212, v187, v187
	v_add_f32_e32 v77, v77, v212
	ds_read_b128 v[204:207], v71 offset:15360
	ds_read_b128 v[208:211], v71 offset:48128
	v_lshlrev_b32_e32 v212, 16, v6
	v_and_b32_e32 v213, 0xffff0000, v6
	v_lshlrev_b32_e32 v214, 16, v7
	v_and_b32_e32 v215, 0xffff0000, v7
	v_lshlrev_b32_e32 v216, 16, v8
	v_and_b32_e32 v217, 0xffff0000, v8
	v_lshlrev_b32_e32 v218, 16, v9
	v_and_b32_e32 v219, 0xffff0000, v9
	v_mul_f32_e32 v212, v26, v212
	v_mul_f32_e32 v213, v26, v213
	v_mul_f32_e32 v214, v26, v214
	v_mul_f32_e32 v215, v26, v215
	v_mul_f32_e32 v216, v27, v216
	v_mul_f32_e32 v217, v27, v217
	v_mul_f32_e32 v218, v27, v218
	v_mul_f32_e32 v219, v27, v219
	s_waitcnt lgkmcnt(2)
	v_mul_f32_e32 v188, v212, v200
	v_mul_f32_e32 v189, v213, v201
	v_mul_f32_e32 v190, v214, v202
	v_mul_f32_e32 v191, v215, v203
	v_fmac_f32_e32 v188, v196, v216
	v_fmac_f32_e32 v189, v197, v217
	v_fmac_f32_e32 v190, v198, v218
	v_fmac_f32_e32 v191, v199, v219
	v_mul_f32_e32 v212, v189, v189
	v_fmac_f32_e32 v212, v188, v188
	v_fmac_f32_e32 v212, v190, v190
	v_fmac_f32_e32 v212, v191, v191
	v_add_f32_e32 v77, v77, v212
	v_lshlrev_b32_e32 v212, 16, v2
	v_and_b32_e32 v213, 0xffff0000, v2
	v_lshlrev_b32_e32 v214, 16, v3
	v_and_b32_e32 v215, 0xffff0000, v3
	v_lshlrev_b32_e32 v216, 16, v4
	v_and_b32_e32 v217, 0xffff0000, v4
	v_lshlrev_b32_e32 v218, 16, v5
	v_and_b32_e32 v219, 0xffff0000, v5
	v_mul_f32_e32 v212, v26, v212
	v_mul_f32_e32 v213, v26, v213
	v_mul_f32_e32 v214, v26, v214
	v_mul_f32_e32 v215, v26, v215
	v_mul_f32_e32 v216, v27, v216
	v_mul_f32_e32 v217, v27, v217
	v_mul_f32_e32 v218, v27, v218
	v_mul_f32_e32 v219, v27, v219
	s_waitcnt lgkmcnt(0)
	v_mul_f32_e32 v192, v212, v208
	v_mul_f32_e32 v193, v213, v209
	v_mul_f32_e32 v194, v214, v210
	v_mul_f32_e32 v195, v215, v211
	v_fmac_f32_e32 v192, v204, v216
	v_fmac_f32_e32 v193, v205, v217
	v_fmac_f32_e32 v194, v206, v218
	v_fmac_f32_e32 v195, v207, v219
	v_mul_f32_e32 v212, v193, v193
	v_fmac_f32_e32 v212, v192, v192
	v_fmac_f32_e32 v212, v194, v194
	v_fmac_f32_e32 v212, v195, v195
	v_add_f32_e32 v77, v77, v212
	ds_bpermute_b32 v70, v70, v77
	s_waitcnt lgkmcnt(0)
	v_add_f32_e32 v70, v77, v70
	ds_bpermute_b32 v72, v72, v70
	s_waitcnt lgkmcnt(0)
	v_add_f32_e32 v70, v70, v72
	ds_bpermute_b32 v72, v73, v70
	s_waitcnt lgkmcnt(0)
	v_add_f32_e32 v70, v70, v72
	ds_bpermute_b32 v72, v74, v70
	s_waitcnt lgkmcnt(0)
	v_add_f32_e32 v70, v70, v72
	ds_bpermute_b32 v72, v75, v70
	s_waitcnt lgkmcnt(0)
	v_add_f32_e32 v70, v70, v72
	ds_bpermute_b32 v72, v76, v70
	s_waitcnt lgkmcnt(0)
	v_add_f32_e32 v70, v70, v72
	v_fmamk_f32 v70, v70, 0x39800000, v100
	v_mul_f32_e32 v72, 0x4b800000, v70
	v_cmp_gt_f32_e32 vcc, s66, v70
	s_nop 1
	v_cndmask_b32_e32 v70, v70, v72, vcc
	v_rsq_f32_e32 v70, v70
	s_nop 0
	v_mul_f32_e32 v72, 0x45800000, v70
	v_cndmask_b32_e32 v70, v70, v72, vcc
	s_and_saveexec_b64 s[6:7], s[4:5]
	s_cbranch_execz .LBB0_1118
	global_store_dword v79, v70, s[62:63]
	s_branch .LBB0_1118

; #define LAS __attribute__((address_space(3)))
; template <int MODE> ...
;     ...
;     __syncthreads();
; #pragma unroll
;     for (int i = 0; i < 2; ++i) { const int o = 4 * (tid + NTHREADS * i);
;         if (MODE != 0) { *(LAS f32x4*)(GP + o) = *(const f32x4*)(gpost + o); const f32x4 g = *(const f32x4*)(gprev + o); *(LAS f32x4*)(GI + o) = (f32x4){1.f / g.x, 1.f / g.y, 1.f / g.z, 1.f / g.w}; }
;         if (MODE != 2) *(LAS f32x4*)(GN + o) = *(const f32x4*)(gpre + o); }
;     __syncthreads();
;     const int lo4 = 4 * lane;
; #pragma unroll 1
;     for (int row = gw; row < SEQ; row += NGW) {
.LBB0_1610:
	s_cmp_gt_i32 s36, 14
	s_cselect_b64 s[6:7], -1, 0
	s_xor_b64 s[4:5], s[4:5], -1
	s_or_b64 s[4:5], s[6:7], s[4:5]
	s_and_b64 vcc, exec, s[4:5]
	s_cbranch_vccnz .LBB0_1616
	s_mov_b64 s[12:13], 0
	s_waitcnt vmcnt(0)
	v_mbcnt_lo_u32_b32 v2, -1, 0
	v_mbcnt_hi_u32_b32 v2, -1, v2
	s_load_dwordx4 s[4:7], s[0:1], 0xa8
	s_load_dwordx2 s[8:9], s[0:1], 0x10
	v_lshlrev_b32_e32 v0, 2, v2
	v_lshl_add_u32 v24, s89, 8, v0
	v_ashrrev_i32_e32 v25, 31, v24
	v_lshlrev_b64 v[20:21], 2, v[24:25]
	v_add_u32_e32 v12, 0x800, v24
	s_waitcnt lgkmcnt(0)
	v_lshl_add_u64 v[8:9], s[4:5], 0, v[20:21]
	v_ashrrev_i32_e32 v13, 31, v12
	s_barrier
	v_lshl_add_u64 v[4:5], s[6:7], 0, v[20:21]
	global_load_dwordx4 v[8:11], v[8:9], off
	v_lshlrev_b64 v[26:27], 2, v[12:13]
	global_load_dwordx4 v[4:7], v[4:5], off
	v_lshl_add_u64 v[12:13], s[6:7], 0, v[26:27]
	v_lshl_add_u64 v[16:17], s[4:5], 0, v[26:27]
	global_load_dwordx4 v[12:15], v[12:13], off
	s_add_u32 s4, s8, 0x4000
	global_load_dwordx4 v[16:19], v[16:17], off
	s_addc_u32 s5, s9, 0
	v_lshl_add_u64 v[20:21], s[4:5], 0, v[20:21]
	global_load_dwordx4 v[20:23], v[20:21], off
	v_lshl_add_u32 v1, v24, 2, 0
	v_lshl_add_u64 v[24:25], s[4:5], 0, v[26:27]
	global_load_dwordx4 v[24:27], v[24:25], off
	s_cmpk_gt_i32 s40, 0x1fff
	s_waitcnt vmcnt(5)
	v_div_scale_f32 v3, s[4:5], v8, v8, 1.0
	s_waitcnt vmcnt(4)
	ds_write_b128 v1, v[4:7]
	v_div_scale_f32 v5, s[4:5], v9, v9, 1.0
	v_rcp_f32_e32 v31, v3
	v_div_scale_f32 v7, s[6:7], v10, v10, 1.0
	v_rcp_f32_e32 v32, v5
	s_waitcnt vmcnt(3)
	ds_write_b128 v1, v[12:15] offset:8192
	s_waitcnt vmcnt(2)
	v_div_scale_f32 v12, s[10:11], v16, v16, 1.0
	v_div_scale_f32 v29, s[8:9], v11, v11, 1.0
	v_rcp_f32_e32 v33, v7
	v_rcp_f32_e32 v15, v12
	v_rcp_f32_e32 v34, v29
	s_waitcnt vmcnt(1)
	ds_write_b128 v1, v[20:23] offset:16384
	v_fma_f32 v21, -v3, v31, 1.0
	v_div_scale_f32 v4, vcc, 1.0, v8, 1.0
	v_fma_f32 v22, -v5, v32, 1.0
	v_fmac_f32_e32 v31, v21, v31
	v_div_scale_f32 v6, s[4:5], 1.0, v9, 1.0
	v_fma_f32 v23, -v7, v33, 1.0
	v_fmac_f32_e32 v32, v22, v32
	v_fma_f32 v21, -v12, v15, 1.0
	v_mul_f32_e32 v22, v4, v31
	v_div_scale_f32 v28, s[6:7], 1.0, v10, 1.0
	v_fma_f32 v35, -v29, v34, 1.0
	v_fmac_f32_e32 v33, v23, v33
	v_mul_f32_e32 v23, v6, v32
	v_fmac_f32_e32 v15, v21, v15
	v_fma_f32 v21, -v3, v22, v4
	v_div_scale_f32 v30, s[8:9], 1.0, v11, 1.0
	v_fmac_f32_e32 v34, v35, v34
	v_mul_f32_e32 v35, v28, v33
	v_fma_f32 v37, -v5, v23, v6
	v_fmac_f32_e32 v22, v21, v31
	v_div_scale_f32 v13, s[10:11], 1.0, v16, 1.0
	v_mul_f32_e32 v36, v30, v34
	v_fma_f32 v38, -v7, v35, v28
	v_fmac_f32_e32 v23, v37, v32
	v_fma_f32 v3, -v3, v22, v4
	v_div_scale_f32 v14, s[14:15], v17, v17, 1.0
	v_fma_f32 v39, -v29, v36, v30
	v_mul_f32_e32 v40, v13, v15
	v_fmac_f32_e32 v35, v38, v33
	v_fma_f32 v5, -v5, v23, v6
	v_div_fmas_f32 v3, v3, v31, v22
	s_mov_b64 vcc, s[4:5]
	v_rcp_f32_e32 v20, v14
	v_fmac_f32_e32 v36, v39, v34
	v_fma_f32 v21, -v12, v40, v13
	v_fma_f32 v6, -v7, v35, v28
	v_div_fixup_f32 v4, v3, v8, 1.0
	v_div_fmas_f32 v3, v5, v32, v23
	s_mov_b64 vcc, s[6:7]
	v_fma_f32 v7, -v29, v36, v30
	v_fmac_f32_e32 v40, v21, v15
	v_div_fixup_f32 v5, v3, v9, 1.0
	v_div_fmas_f32 v3, v6, v33, v35
	s_mov_b64 vcc, s[8:9]
	v_fma_f32 v12, -v12, v40, v13
	v_div_fixup_f32 v6, v3, v10, 1.0
	v_div_fmas_f32 v3, v7, v34, v36
	s_mov_b64 vcc, s[10:11]
	v_div_fixup_f32 v7, v3, v11, 1.0
	v_div_fmas_f32 v3, v12, v15, v40
	ds_write_b128 v1, v[4:7] offset:32768
	v_div_fixup_f32 v4, v3, v16, 1.0
	v_fma_f32 v3, -v14, v20, 1.0
	v_fmac_f32_e32 v20, v3, v20
	v_div_scale_f32 v3, vcc, 1.0, v17, 1.0
	v_mul_f32_e32 v5, v3, v20
	v_fma_f32 v6, -v14, v5, v3
	v_fmac_f32_e32 v5, v6, v20
	v_div_scale_f32 v6, s[4:5], v18, v18, 1.0
	v_rcp_f32_e32 v7, v6
	v_fma_f32 v3, -v14, v5, v3
	v_div_fmas_f32 v3, v3, v20, v5
	v_div_fixup_f32 v5, v3, v17, 1.0
	v_fma_f32 v3, -v6, v7, 1.0
	v_fmac_f32_e32 v7, v3, v7
	v_div_scale_f32 v3, vcc, 1.0, v18, 1.0
	v_mul_f32_e32 v8, v3, v7
	v_fma_f32 v9, -v6, v8, v3
	v_fmac_f32_e32 v8, v9, v7
	v_div_scale_f32 v9, s[4:5], v19, v19, 1.0
	v_rcp_f32_e32 v10, v9
	v_fma_f32 v3, -v6, v8, v3
	v_div_fmas_f32 v3, v3, v7, v8
	v_div_fixup_f32 v6, v3, v18, 1.0
	v_fma_f32 v3, -v9, v10, 1.0
	v_fmac_f32_e32 v10, v3, v10
	v_div_scale_f32 v3, vcc, 1.0, v19, 1.0
	v_mul_f32_e32 v7, v3, v10
	v_fma_f32 v8, -v9, v7, v3
	v_fmac_f32_e32 v7, v8, v10
	v_fma_f32 v3, -v9, v7, v3
	v_div_fmas_f32 v3, v3, v10, v7
	v_div_fixup_f32 v7, v3, v19, 1.0
	ds_write_b128 v1, v[4:7] offset:40960
	s_waitcnt vmcnt(0)
	ds_write_b128 v1, v[24:27] offset:24576
	s_waitcnt lgkmcnt(0)
	s_barrier
	s_cbranch_scc1 .LBB0_1616
	s_load_dwordx2 s[6:7], s[0:1], 0xe8
	s_ashr_i32 s41, s40, 31
	s_lshl_b64 s[8:9], s[40:41], 2
	v_ashrrev_i32_e32 v1, 31, v0
	v_cmp_eq_u32_e64 s[4:5], 0, v2
	s_waitcnt lgkmcnt(0)
	s_add_u32 s8, s6, s8
	s_addc_u32 s9, s7, s9
	s_add_u32 s64, s8, 0x2c0000
	s_addc_u32 s65, s9, 0
	s_ashr_i32 s39, s38, 31
	s_lshl_b64 s[8:9], s[38:39], 2
	s_lshl_b64 s[10:11], s[40:41], 13
	s_add_u32 s6, s6, s10
	s_addc_u32 s7, s7, s11
	v_mbcnt_lo_u32_b32 v2, -1, 0
	v_lshl_add_u32 v71, v0, 2, 0
	v_lshl_add_u64 v[0:1], v[0:1], 1, s[6:7]
	s_lshl_b64 s[10:11], s[38:39], 13
	s_mov_b64 s[14:15], 0x3000000
	s_mov_b64 s[18:19], 0x3000200
	s_mov_b64 s[20:21], 0x3000400
	s_mov_b64 s[22:23], 0x3000600
	s_mov_b64 s[24:25], 0x3000800
	s_mov_b64 s[26:27], 0x3000a00
	s_mov_b64 s[42:43], 0x3000c00
	s_mov_b64 s[44:45], 0x3000e00
	s_mov_b64 s[46:47], 0x3001000
	s_mov_b32 s39, 0x3001000
	s_mov_b32 s41, 0x7001000
	s_mov_b64 s[48:49], 0x3001200
	s_mov_b64 s[50:51], 0x3001400
	s_mov_b64 s[52:53], 0x3001600
	s_mov_b64 s[54:55], 0x3001800
	s_mov_b64 s[56:57], 0x3001a00
	s_mov_b64 s[58:59], 0x3001c00
	s_mov_b64 s[60:61], 0x3001e00
	v_mov_b32_e32 v98, 0
	v_mov_b32_e32 v99, 0x358637bd
	s_mov_b32 s66, 0x800000
	v_mbcnt_hi_u32_b32 v100, -1, v2
	s_mov_b32 s67, s40
	s_mov_b32 s96, 0x3000000
	s_mov_b32 s97, 0x3001000
	s_branch .LBB0_1614

; #define LAS __attribute__((address_space(3)))
; template <int MODE> ...
;     ...
;     __syncthreads();
; #pragma unroll
;     for (int i = 0; i < 2; ++i) { const int o = 4 * (tid + NTHREADS * i);
;         if (MODE != 0) { *(LAS f32x4*)(GP + o) = *(const f32x4*)(gpost + o); const f32x4 g = *(const f32x4*)(gprev + o); *(LAS f32x4*)(GI + o) = (f32x4){1.f / g.x, 1.f / g.y, 1.f / g.z, 1.f / g.w}; }
;         if (MODE != 2) *(LAS f32x4*)(GN + o) = *(const f32x4*)(gpre + o); }
;     __syncthreads();
;     const int lo4 = 4 * lane;
; #pragma unroll 1
;     for (int row = gw; row < SEQ; row += NGW) {
.LBB0_1984:
	s_cmp_gt_i32 s36, 18
	s_cselect_b64 s[6:7], -1, 0
	s_xor_b64 s[4:5], s[4:5], -1
	s_or_b64 s[4:5], s[6:7], s[4:5]
	s_and_b64 vcc, exec, s[4:5]
	s_cbranch_vccnz .LBB0_1990
	s_mov_b64 s[12:13], 0
	s_waitcnt vmcnt(0)
	v_mbcnt_lo_u32_b32 v2, -1, 0
	v_mbcnt_hi_u32_b32 v2, -1, v2
	s_load_dwordx4 s[4:7], s[0:1], 0x10
	s_load_dwordx2 s[8:9], s[0:1], 0x70
	v_lshlrev_b32_e32 v0, 2, v2
	v_lshl_add_u32 v24, s89, 8, v0
	v_ashrrev_i32_e32 v25, 31, v24
	s_waitcnt lgkmcnt(0)
	s_add_u32 s4, s4, 0x4000
	s_addc_u32 s5, s5, 0
	v_lshlrev_b64 v[20:21], 2, v[24:25]
	v_lshl_add_u64 v[4:5], s[4:5], 0, v[20:21]
	v_add_u32_e32 v8, 0x800, v24
	s_barrier
	global_load_dwordx4 v[4:7], v[4:5], off
	v_ashrrev_i32_e32 v9, 31, v8
	v_lshlrev_b64 v[26:27], 2, v[8:9]
	v_lshl_add_u64 v[8:9], s[4:5], 0, v[26:27]
	s_add_u32 s4, s6, 0x4000
	s_addc_u32 s5, s7, 0
	s_add_u32 s6, s8, 0x4000
	v_lshl_add_u64 v[22:23], s[4:5], 0, v[20:21]
	global_load_dwordx4 v[8:11], v[8:9], off
	v_lshl_add_u64 v[28:29], s[4:5], 0, v[26:27]
	s_addc_u32 s7, s9, 0
	global_load_dwordx4 v[12:15], v[22:23], off
	global_load_dwordx4 v[16:19], v[28:29], off
	v_lshl_add_u64 v[20:21], s[6:7], 0, v[20:21]
	global_load_dwordx4 v[20:23], v[20:21], off
	v_lshl_add_u32 v1, v24, 2, 0
	v_lshl_add_u64 v[24:25], s[6:7], 0, v[26:27]
	global_load_dwordx4 v[24:27], v[24:25], off
	s_cmpk_gt_i32 s40, 0x1fff
	s_waitcnt vmcnt(3)
	ds_write_b128 v1, v[12:15]
	s_waitcnt vmcnt(2)
	ds_write_b128 v1, v[16:19] offset:8192
	s_waitcnt vmcnt(1)
	ds_write_b128 v1, v[20:23] offset:16384
	v_div_scale_f32 v3, s[4:5], v4, v4, 1.0
	v_div_scale_f32 v29, s[4:5], v5, v5, 1.0
	v_rcp_f32_e32 v37, v3
	v_div_scale_f32 v31, s[6:7], v6, v6, 1.0
	v_rcp_f32_e32 v38, v29
	v_div_scale_f32 v33, s[8:9], v7, v7, 1.0
	v_rcp_f32_e32 v39, v31
	v_rcp_f32_e32 v40, v33
	v_fma_f32 v12, -v3, v37, 1.0
	v_div_scale_f32 v28, vcc, 1.0, v4, 1.0
	v_fma_f32 v13, -v29, v38, 1.0
	v_fmac_f32_e32 v37, v12, v37
	v_div_scale_f32 v30, s[4:5], 1.0, v5, 1.0
	v_fma_f32 v14, -v31, v39, 1.0
	v_fmac_f32_e32 v38, v13, v38
	v_mul_f32_e32 v12, v28, v37
	v_div_scale_f32 v32, s[6:7], 1.0, v6, 1.0
	v_fma_f32 v15, -v33, v40, 1.0
	v_fmac_f32_e32 v39, v14, v39
	v_mul_f32_e32 v13, v30, v38
	v_fma_f32 v17, -v3, v12, v28
	v_div_scale_f32 v34, s[8:9], 1.0, v7, 1.0
	v_fmac_f32_e32 v40, v15, v40
	v_mul_f32_e32 v14, v32, v39
	v_fma_f32 v18, -v29, v13, v30
	v_fmac_f32_e32 v12, v17, v37
	v_div_scale_f32 v35, s[10:11], v8, v8, 1.0
	v_mul_f32_e32 v15, v34, v40
	v_fma_f32 v19, -v31, v14, v32
	v_fmac_f32_e32 v13, v18, v38
	v_fma_f32 v3, -v3, v12, v28
	v_rcp_f32_e32 v41, v35
	v_fma_f32 v20, -v33, v15, v34
	v_fmac_f32_e32 v14, v19, v39
	v_fma_f32 v17, -v29, v13, v30
	v_div_fmas_f32 v3, v3, v37, v12
	s_mov_b64 vcc, s[4:5]
	v_fmac_f32_e32 v15, v20, v40
	v_fma_f32 v18, -v31, v14, v32
	v_div_fixup_f32 v4, v3, v4, 1.0
	v_div_fmas_f32 v3, v17, v38, v13
	s_mov_b64 vcc, s[6:7]
	v_fma_f32 v19, -v33, v15, v34
	v_div_fixup_f32 v5, v3, v5, 1.0
	v_div_fmas_f32 v3, v18, v39, v14
	s_mov_b64 vcc, s[8:9]
	v_div_fixup_f32 v6, v3, v6, 1.0
	v_div_fmas_f32 v3, v19, v40, v15
	v_fma_f32 v16, -v35, v41, 1.0
	v_div_fixup_f32 v7, v3, v7, 1.0
	v_div_scale_f32 v3, s[4:5], v9, v9, 1.0
	v_div_scale_f32 v36, s[10:11], 1.0, v8, 1.0
	v_fmac_f32_e32 v41, v16, v41
	ds_write_b128 v1, v[4:7] offset:32768
	v_rcp_f32_e32 v5, v3
	v_mul_f32_e32 v16, v36, v41
	v_fma_f32 v21, -v35, v16, v36
	v_fmac_f32_e32 v16, v21, v41
	v_fma_f32 v20, -v35, v16, v36
	s_mov_b64 vcc, s[10:11]
	v_fma_f32 v6, -v3, v5, 1.0
	v_div_fmas_f32 v4, v20, v41, v16
	v_fmac_f32_e32 v5, v6, v5
	v_div_scale_f32 v6, vcc, 1.0, v9, 1.0
	v_mul_f32_e32 v7, v6, v5
	v_div_fixup_f32 v4, v4, v8, 1.0
	v_fma_f32 v8, -v3, v7, v6
	v_fmac_f32_e32 v7, v8, v5
	v_fma_f32 v3, -v3, v7, v6
	v_div_scale_f32 v6, s[4:5], v10, v10, 1.0
	v_rcp_f32_e32 v8, v6
	v_div_fmas_f32 v3, v3, v5, v7
	v_div_fixup_f32 v5, v3, v9, 1.0
	v_fma_f32 v3, -v6, v8, 1.0
	v_fmac_f32_e32 v8, v3, v8
	v_div_scale_f32 v3, vcc, 1.0, v10, 1.0
	v_mul_f32_e32 v7, v3, v8
	v_fma_f32 v9, -v6, v7, v3
	v_fmac_f32_e32 v7, v9, v8
	v_div_scale_f32 v9, s[4:5], v11, v11, 1.0
	v_rcp_f32_e32 v12, v9
	v_fma_f32 v3, -v6, v7, v3
	v_div_fmas_f32 v3, v3, v8, v7
	v_div_fixup_f32 v6, v3, v10, 1.0
	v_fma_f32 v3, -v9, v12, 1.0
	v_fmac_f32_e32 v12, v3, v12
	v_div_scale_f32 v3, vcc, 1.0, v11, 1.0
	v_mul_f32_e32 v7, v3, v12
	v_fma_f32 v8, -v9, v7, v3
	v_fmac_f32_e32 v7, v8, v12
	v_fma_f32 v3, -v9, v7, v3
	v_div_fmas_f32 v3, v3, v12, v7
	v_div_fixup_f32 v7, v3, v11, 1.0
	ds_write_b128 v1, v[4:7] offset:40960
	s_waitcnt vmcnt(0)
	ds_write_b128 v1, v[24:27] offset:24576
	s_waitcnt lgkmcnt(0)
	s_barrier
	s_cbranch_scc1 .LBB0_1990
	s_load_dwordx2 s[6:7], s[0:1], 0xe8
	s_ashr_i32 s41, s40, 31
	s_lshl_b64 s[8:9], s[40:41], 2
	v_ashrrev_i32_e32 v1, 31, v0
	v_cmp_eq_u32_e64 s[4:5], 0, v2
	s_waitcnt lgkmcnt(0)
	s_add_u32 s8, s6, s8
	s_addc_u32 s9, s7, s9
	s_add_u32 s64, s8, 0x2c0000
	s_addc_u32 s65, s9, 0
	s_ashr_i32 s39, s38, 31
	s_lshl_b64 s[8:9], s[38:39], 2
	s_lshl_b64 s[10:11], s[40:41], 13
	s_add_u32 s6, s6, s10
	s_addc_u32 s7, s7, s11
	v_mbcnt_lo_u32_b32 v2, -1, 0
	v_lshl_add_u32 v71, v0, 2, 0
	v_lshl_add_u64 v[0:1], v[0:1], 1, s[6:7]
	s_lshl_b64 s[10:11], s[38:39], 13
	s_mov_b64 s[14:15], 0x3000000
	s_mov_b64 s[18:19], 0x3000200
	s_mov_b64 s[20:21], 0x3000400
	s_mov_b64 s[22:23], 0x3000600
	s_mov_b64 s[24:25], 0x3000800
	s_mov_b64 s[26:27], 0x3000a00
	s_mov_b64 s[42:43], 0x3000c00
	s_mov_b64 s[44:45], 0x3000e00
	s_mov_b64 s[46:47], 0x3001000
	s_mov_b32 s39, 0x3001000
	s_mov_b32 s41, 0x7001000
	s_mov_b64 s[48:49], 0x3001200
	s_mov_b64 s[50:51], 0x3001400
	s_mov_b64 s[52:53], 0x3001600
	s_mov_b64 s[54:55], 0x3001800
	s_mov_b64 s[56:57], 0x3001a00
	s_mov_b64 s[58:59], 0x3001c00
	s_mov_b64 s[60:61], 0x3001e00
	v_mov_b32_e32 v79, 0
	v_mov_b32_e32 v100, 0x358637bd
	s_mov_b32 s66, 0x800000
	v_mbcnt_hi_u32_b32 v101, -1, v2
	s_mov_b32 s67, s40
	s_mov_b32 s96, 0x3000000
	s_mov_b32 s97, 0x3001000
	s_branch .LBB0_1988

; #define LAS __attribute__((address_space(3)))
; template <int MODE> ...
;     ...
;     __syncthreads();
; #pragma unroll
;     for (int i = 0; i < 2; ++i) { const int o = 4 * (tid + NTHREADS * i);
;         if (MODE != 0) { *(LAS f32x4*)(GP + o) = *(const f32x4*)(gpost + o); const f32x4 g = *(const f32x4*)(gprev + o); *(LAS f32x4*)(GI + o) = (f32x4){1.f / g.x, 1.f / g.y, 1.f / g.z, 1.f / g.w}; }
;         if (MODE != 2) *(LAS f32x4*)(GN + o) = *(const f32x4*)(gpre + o); }
;     __syncthreads();
;     const int lo4 = 4 * lane;
; #pragma unroll 1
;     for (int row = gw; row < SEQ; row += NGW) {
.LBB0_2327:
	s_cmp_gt_i32 s36, 22
	s_cselect_b64 s[6:7], -1, 0
	s_xor_b64 s[4:5], s[4:5], -1
	s_or_b64 s[4:5], s[6:7], s[4:5]
	s_and_b64 vcc, exec, s[4:5]
	s_cbranch_vccnz .LBB0_2333
	s_mov_b64 s[12:13], 0
	s_waitcnt vmcnt(0)
	v_mbcnt_lo_u32_b32 v2, -1, 0
	v_mbcnt_hi_u32_b32 v2, -1, v2
	s_load_dwordx4 s[4:7], s[0:1], 0x70
	s_load_dwordx2 s[8:9], s[0:1], 0xa8
	v_lshlrev_b32_e32 v0, 2, v2
	v_lshl_add_u32 v24, s89, 8, v0
	v_ashrrev_i32_e32 v25, 31, v24
	s_waitcnt lgkmcnt(0)
	s_add_u32 s4, s4, 0x4000
	s_addc_u32 s5, s5, 0
	v_lshlrev_b64 v[20:21], 2, v[24:25]
	v_lshl_add_u64 v[4:5], s[4:5], 0, v[20:21]
	v_add_u32_e32 v8, 0x800, v24
	s_barrier
	global_load_dwordx4 v[4:7], v[4:5], off
	v_ashrrev_i32_e32 v9, 31, v8
	v_lshlrev_b64 v[26:27], 2, v[8:9]
	v_lshl_add_u64 v[8:9], s[4:5], 0, v[26:27]
	s_add_u32 s4, s6, 0x4000
	s_addc_u32 s5, s7, 0
	s_add_u32 s6, s8, 0x4000
	v_lshl_add_u64 v[22:23], s[4:5], 0, v[20:21]
	global_load_dwordx4 v[8:11], v[8:9], off
	v_lshl_add_u64 v[28:29], s[4:5], 0, v[26:27]
	s_addc_u32 s7, s9, 0
	global_load_dwordx4 v[12:15], v[22:23], off
	global_load_dwordx4 v[16:19], v[28:29], off
	v_lshl_add_u64 v[20:21], s[6:7], 0, v[20:21]
	global_load_dwordx4 v[20:23], v[20:21], off
	v_lshl_add_u32 v1, v24, 2, 0
	v_lshl_add_u64 v[24:25], s[6:7], 0, v[26:27]
	global_load_dwordx4 v[24:27], v[24:25], off
	s_cmpk_gt_i32 s40, 0x1fff
	s_waitcnt vmcnt(3)
	ds_write_b128 v1, v[12:15]
	s_waitcnt vmcnt(2)
	ds_write_b128 v1, v[16:19] offset:8192
	s_waitcnt vmcnt(1)
	ds_write_b128 v1, v[20:23] offset:16384
	v_div_scale_f32 v3, s[4:5], v4, v4, 1.0
	v_div_scale_f32 v29, s[4:5], v5, v5, 1.0
	v_rcp_f32_e32 v37, v3
	v_div_scale_f32 v31, s[6:7], v6, v6, 1.0
	v_rcp_f32_e32 v38, v29
	v_div_scale_f32 v33, s[8:9], v7, v7, 1.0
	v_rcp_f32_e32 v39, v31
	v_rcp_f32_e32 v40, v33
	v_fma_f32 v12, -v3, v37, 1.0
	v_div_scale_f32 v28, vcc, 1.0, v4, 1.0
	v_fma_f32 v13, -v29, v38, 1.0
	v_fmac_f32_e32 v37, v12, v37
	v_div_scale_f32 v30, s[4:5], 1.0, v5, 1.0
	v_fma_f32 v14, -v31, v39, 1.0
	v_fmac_f32_e32 v38, v13, v38
	v_mul_f32_e32 v12, v28, v37
	v_div_scale_f32 v32, s[6:7], 1.0, v6, 1.0
	v_fma_f32 v15, -v33, v40, 1.0
	v_fmac_f32_e32 v39, v14, v39
	v_mul_f32_e32 v13, v30, v38
	v_fma_f32 v17, -v3, v12, v28
	v_div_scale_f32 v34, s[8:9], 1.0, v7, 1.0
	v_fmac_f32_e32 v40, v15, v40
	v_mul_f32_e32 v14, v32, v39
	v_fma_f32 v18, -v29, v13, v30
	v_fmac_f32_e32 v12, v17, v37
	v_div_scale_f32 v35, s[10:11], v8, v8, 1.0
	v_mul_f32_e32 v15, v34, v40
	v_fma_f32 v19, -v31, v14, v32
	v_fmac_f32_e32 v13, v18, v38
	v_fma_f32 v3, -v3, v12, v28
	v_rcp_f32_e32 v41, v35
	v_fma_f32 v20, -v33, v15, v34
	v_fmac_f32_e32 v14, v19, v39
	v_fma_f32 v17, -v29, v13, v30
	v_div_fmas_f32 v3, v3, v37, v12
	s_mov_b64 vcc, s[4:5]
	v_fmac_f32_e32 v15, v20, v40
	v_fma_f32 v18, -v31, v14, v32
	v_div_fixup_f32 v4, v3, v4, 1.0
	v_div_fmas_f32 v3, v17, v38, v13
	s_mov_b64 vcc, s[6:7]
	v_fma_f32 v19, -v33, v15, v34
	v_div_fixup_f32 v5, v3, v5, 1.0
	v_div_fmas_f32 v3, v18, v39, v14
	s_mov_b64 vcc, s[8:9]
	v_div_fixup_f32 v6, v3, v6, 1.0
	v_div_fmas_f32 v3, v19, v40, v15
	v_fma_f32 v16, -v35, v41, 1.0
	v_div_fixup_f32 v7, v3, v7, 1.0
	v_div_scale_f32 v3, s[4:5], v9, v9, 1.0
	v_div_scale_f32 v36, s[10:11], 1.0, v8, 1.0
	v_fmac_f32_e32 v41, v16, v41
	ds_write_b128 v1, v[4:7] offset:32768
	v_rcp_f32_e32 v5, v3
	v_mul_f32_e32 v16, v36, v41
	v_fma_f32 v21, -v35, v16, v36
	v_fmac_f32_e32 v16, v21, v41
	v_fma_f32 v20, -v35, v16, v36
	s_mov_b64 vcc, s[10:11]
	v_fma_f32 v6, -v3, v5, 1.0
	v_div_fmas_f32 v4, v20, v41, v16
	v_fmac_f32_e32 v5, v6, v5
	v_div_scale_f32 v6, vcc, 1.0, v9, 1.0
	v_mul_f32_e32 v7, v6, v5
	v_div_fixup_f32 v4, v4, v8, 1.0
	v_fma_f32 v8, -v3, v7, v6
	v_fmac_f32_e32 v7, v8, v5
	v_fma_f32 v3, -v3, v7, v6
	v_div_scale_f32 v6, s[4:5], v10, v10, 1.0
	v_rcp_f32_e32 v8, v6
	v_div_fmas_f32 v3, v3, v5, v7
	v_div_fixup_f32 v5, v3, v9, 1.0
	v_fma_f32 v3, -v6, v8, 1.0
	v_fmac_f32_e32 v8, v3, v8
	v_div_scale_f32 v3, vcc, 1.0, v10, 1.0
	v_mul_f32_e32 v7, v3, v8
	v_fma_f32 v9, -v6, v7, v3
	v_fmac_f32_e32 v7, v9, v8
	v_div_scale_f32 v9, s[4:5], v11, v11, 1.0
	v_rcp_f32_e32 v12, v9
	v_fma_f32 v3, -v6, v7, v3
	v_div_fmas_f32 v3, v3, v8, v7
	v_div_fixup_f32 v6, v3, v10, 1.0
	v_fma_f32 v3, -v9, v12, 1.0
	v_fmac_f32_e32 v12, v3, v12
	v_div_scale_f32 v3, vcc, 1.0, v11, 1.0
	v_mul_f32_e32 v7, v3, v12
	v_fma_f32 v8, -v9, v7, v3
	v_fmac_f32_e32 v7, v8, v12
	v_fma_f32 v3, -v9, v7, v3
	v_div_fmas_f32 v3, v3, v12, v7
	v_div_fixup_f32 v7, v3, v11, 1.0
	ds_write_b128 v1, v[4:7] offset:40960
	s_waitcnt vmcnt(0)
	ds_write_b128 v1, v[24:27] offset:24576
	s_waitcnt lgkmcnt(0)
	s_barrier
	s_cbranch_scc1 .LBB0_2333
	s_load_dwordx2 s[6:7], s[0:1], 0xe8
	s_ashr_i32 s41, s40, 31
	s_lshl_b64 s[8:9], s[40:41], 2
	v_ashrrev_i32_e32 v1, 31, v0
	v_cmp_eq_u32_e64 s[4:5], 0, v2
	s_waitcnt lgkmcnt(0)
	s_add_u32 s8, s6, s8
	s_addc_u32 s9, s7, s9
	s_add_u32 s64, s8, 0x2c0000
	s_addc_u32 s65, s9, 0
	s_ashr_i32 s39, s38, 31
	s_lshl_b64 s[8:9], s[38:39], 2
	s_lshl_b64 s[10:11], s[40:41], 13
	s_add_u32 s6, s6, s10
	s_addc_u32 s7, s7, s11
	v_mbcnt_lo_u32_b32 v2, -1, 0
	v_lshl_add_u32 v71, v0, 2, 0
	v_lshl_add_u64 v[0:1], v[0:1], 1, s[6:7]
	s_lshl_b64 s[10:11], s[38:39], 13
	s_mov_b64 s[14:15], 0x3000000
	s_mov_b64 s[18:19], 0x3000200
	s_mov_b64 s[20:21], 0x3000400
	s_mov_b64 s[22:23], 0x3000600
	s_mov_b64 s[24:25], 0x3000800
	s_mov_b64 s[26:27], 0x3000a00
	s_mov_b64 s[42:43], 0x3000c00
	s_mov_b64 s[44:45], 0x3000e00
	s_mov_b64 s[46:47], 0x3001000
	s_mov_b32 s39, 0x3001000
	s_mov_b32 s41, 0x7001000
	s_mov_b64 s[48:49], 0x3001200
	s_mov_b64 s[50:51], 0x3001400
	s_mov_b64 s[52:53], 0x3001600
	s_mov_b64 s[54:55], 0x3001800
	s_mov_b64 s[56:57], 0x3001a00
	s_mov_b64 s[58:59], 0x3001c00
	s_mov_b64 s[60:61], 0x3001e00
	v_mov_b32_e32 v98, 0
	v_mov_b32_e32 v99, 0x358637bd
	s_mov_b32 s66, 0x800000
	v_mbcnt_hi_u32_b32 v100, -1, v2
	s_mov_b32 s67, s40
	s_mov_b32 s96, 0x3000000
	s_mov_b32 s97, 0x3001000
	s_branch .LBB0_2331
